# plus EpiFFN: dead DPP zero-inits removed, row_ror:15 movs folded into v_fmac_dpp; static hazard re-check (s_nop) over all edits
# speedup vs baseline: 1.0269x; 1.0033x over previous
.LBB0_52:
	s_and_b32 s34, 0xffff, s2
	v_ashrrev_i32_e32 v139, 31, v138
	v_mov_b32_e32 v1, s60
	v_mad_u64_u32 v[2:3], s[0:1], s34, v1, v[138:139]
	s_mov_b64 s[0:1], 0x60000
	s_mul_hi_u32 s11, s31, s34
	s_mul_i32 s10, s31, s34
	v_cmp_gt_i64_e32 vcc, s[0:1], v[2:3]
	s_and_saveexec_b64 s[12:13], vcc
	s_cbranch_execz .LBB0_64
	s_add_u32 s2, s60, s31
	s_addc_u32 s4, 0, 0
	v_mov_b32_e32 v1, s34
	s_mul_i32 s16, s4, s34
	v_mad_u64_u32 v[4:5], s[4:5], s2, v1, v[138:139]
	v_add_u32_e32 v5, s16, v5
	v_cmp_lt_i64_e32 vcc, s[0:1], v[4:5]
	v_mov_b32_e32 v6, 0x60000
	v_cmp_gt_i64_e64 s[0:1], s[0:1], v[4:5]
	v_cndmask_b32_e32 v6, v6, v4, vcc
	v_cndmask_b32_e32 v1, 0, v5, vcc
	v_cndmask_b32_e64 v7, 0, 1, s[0:1]
	v_sub_co_u32_e32 v6, vcc, v6, v7
	s_nop 1
	v_subbrev_co_u32_e32 v7, vcc, 0, v1, vcc
	v_sub_co_u32_e32 v1, vcc, v6, v4
	v_mov_b32_e32 v4, 0
	s_nop 0
	v_subb_co_u32_e32 v8, vcc, v7, v5, vcc
	v_or_b32_e32 v5, s11, v8
	v_cmp_ne_u64_e32 vcc, 0, v[4:5]
	s_and_saveexec_b64 s[4:5], vcc
	s_xor_b64 s[16:17], exec, s[4:5]
	s_cbranch_execz .LBB0_55
	v_cvt_f32_u32_e32 v5, s10
	v_cvt_f32_u32_e32 v6, s11
	s_sub_u32 s2, 0, s10
	s_subb_u32 s18, 0, s11
	v_mov_b32_e32 v11, v4
	v_fmamk_f32 v5, v6, 0x4f800000, v5
	v_rcp_f32_e32 v5, v5
	s_nop 0
	v_mul_f32_e32 v5, 0x5f7ffffc, v5
	v_mul_f32_e32 v6, 0x2f800000, v5
	v_trunc_f32_e32 v6, v6
	v_fmamk_f32 v5, v6, 0xcf800000, v5
	v_cvt_u32_f32_e32 v6, v6
	v_cvt_u32_f32_e32 v5, v5
	v_readfirstlane_b32 s19, v6
	v_readfirstlane_b32 s4, v5
	s_mul_i32 s5, s2, s19
	s_mul_hi_u32 s23, s2, s4
	s_mul_i32 s22, s18, s4
	s_add_i32 s5, s23, s5
	s_mul_i32 s24, s2, s4
	s_add_i32 s5, s5, s22
	s_mul_i32 s23, s4, s5
	s_mul_hi_u32 s25, s4, s24
	s_mul_hi_u32 s22, s4, s5
	s_add_u32 s23, s25, s23
	s_addc_u32 s22, 0, s22
	s_mul_hi_u32 s26, s19, s24
	s_mul_i32 s24, s19, s24
	s_add_u32 s23, s23, s24
	s_mul_hi_u32 s25, s19, s5
	s_addc_u32 s22, s22, s26
	s_addc_u32 s23, s25, 0
	s_mul_i32 s5, s19, s5
	s_add_u32 s5, s22, s5
	s_addc_u32 s22, 0, s23
	s_add_u32 s23, s4, s5
	s_cselect_b64 s[4:5], -1, 0
	s_cmp_lg_u64 s[4:5], 0
	s_addc_u32 s19, s19, s22
	s_mul_i32 s4, s2, s19
	s_mul_hi_u32 s5, s2, s23
	s_add_i32 s4, s5, s4
	s_mul_i32 s18, s18, s23
	s_add_i32 s4, s4, s18
	s_mul_i32 s2, s2, s23
	s_mul_hi_u32 s18, s19, s2
	s_mul_i32 s22, s19, s2
	s_mul_i32 s25, s23, s4
	s_mul_hi_u32 s2, s23, s2
	s_mul_hi_u32 s24, s23, s4
	s_add_u32 s2, s2, s25
	s_addc_u32 s24, 0, s24
	s_add_u32 s2, s2, s22
	s_mul_hi_u32 s5, s19, s4
	s_addc_u32 s2, s24, s18
	s_addc_u32 s5, s5, 0
	s_mul_i32 s4, s19, s4
	s_add_u32 s2, s2, s4
	s_addc_u32 s18, 0, s5
	s_add_u32 s2, s23, s2
	s_cselect_b64 s[4:5], -1, 0
	s_cmp_lg_u64 s[4:5], 0
	s_addc_u32 s18, s19, s18
	v_mad_u64_u32 v[6:7], s[4:5], v1, s18, 0
	v_mul_hi_u32 v10, v1, s2
	v_lshl_add_u64 v[6:7], v[10:11], 0, v[6:7]
	v_mad_u64_u32 v[12:13], s[4:5], v8, s2, 0
	v_add_co_u32_e32 v5, vcc, v6, v12
	v_mad_u64_u32 v[10:11], s[4:5], v8, s18, 0
	s_nop 0
	v_addc_co_u32_e32 v6, vcc, v7, v13, vcc
	v_mov_b32_e32 v7, v4
	s_nop 0
	v_addc_co_u32_e32 v11, vcc, 0, v11, vcc
	v_lshl_add_u64 v[4:5], v[6:7], 0, v[10:11]
	v_mul_lo_u32 v9, s11, v4
	v_mul_lo_u32 v10, s10, v5
	v_mad_u64_u32 v[6:7], s[4:5], s10, v4, 0
	v_add3_u32 v9, v7, v10, v9
	v_sub_u32_e32 v7, v8, v9
	v_mov_b32_e32 v10, s11
	v_sub_co_u32_e32 v1, vcc, v1, v6
	s_nop 1
	v_subb_co_u32_e64 v6, s[4:5], v7, v10, vcc
	v_subrev_co_u32_e64 v7, s[4:5], s10, v1
	v_subb_co_u32_e32 v8, vcc, v8, v9, vcc
	s_nop 0
	s_nop 0
	v_subbrev_co_u32_e64 v6, s[4:5], 0, v6, s[4:5]
	v_cmp_le_u32_e64 s[4:5], s11, v6
	v_cmp_le_u32_e32 vcc, s11, v8
	s_nop 0
	v_cndmask_b32_e64 v10, 0, -1, s[4:5]
	v_cmp_le_u32_e64 s[4:5], s10, v7
	v_cndmask_b32_e64 v9, 0, -1, vcc
	v_cmp_le_u32_e32 vcc, s10, v1
	v_cndmask_b32_e64 v7, 0, -1, s[4:5]
	v_cmp_eq_u32_e64 s[4:5], s11, v6
	v_cndmask_b32_e64 v1, 0, -1, vcc
	v_cmp_eq_u32_e32 vcc, s11, v8
	v_cndmask_b32_e64 v12, v10, v7, s[4:5]
	v_lshl_add_u64 v[6:7], v[4:5], 0, 2
	v_lshl_add_u64 v[10:11], v[4:5], 0, 1
	v_cmp_ne_u32_e64 s[4:5], 0, v12
	v_cndmask_b32_e32 v1, v9, v1, vcc
	v_cmp_ne_u32_e32 vcc, 0, v1
	v_cndmask_b32_e64 v7, v11, v7, s[4:5]
	v_cndmask_b32_e64 v1, v10, v6, s[4:5]
	v_cndmask_b32_e32 v7, v5, v7, vcc
	v_cndmask_b32_e32 v6, v4, v1, vcc

.LBB0_167:
	s_or_b64 exec, exec, s[14:15]
	v_add_u32_e32 v31, 0xffffe000, v40
	v_lshrrev_b32_e32 v31, 12, v31
	v_add_u32_e32 v31, 1, v31
	v_cmp_lt_i32_e32 vcc, s48, v40
	v_mov_b64_e32 v[70:71], s[4:5]
	s_waitcnt vmcnt(3)
	v_mov_b32_e32 v86, v21
	v_cndmask_b32_e32 v31, 0, v31, vcc
	v_add_u32_e32 v31, s69, v31
	v_mad_u64_u32 v[74:75], s[6:7], v31, s50, v[70:71]
	v_lshl_add_u64 v[82:83], v[74:75], 0, s[58:59]
	v_lshl_add_u64 v[84:85], v[74:75], 0, v[164:165]
	v_lshl_add_u64 v[78:79], v[82:83], 0, v[164:165]
	s_nop 0
	v_mov_b32_e32 v252, v78
	v_mov_b32_e32 v253, v79
	global_load_dwordx4 v[198:201], v[28:29], off
	global_load_dwordx4 v[202:205], v[28:29], off offset:1024
	global_load_dwordx4 v[206:209], v[28:29], off offset:2048
	global_load_dwordx4 v[210:213], v[28:29], off offset:3072
	global_load_dwordx4 v[214:217], v[84:85], off
	global_load_dwordx4 v[218:221], v[84:85], off offset:1024
	global_load_dwordx4 v[222:225], v[84:85], off offset:2048
	global_load_dwordx4 v[226:229], v[84:85], off offset:3072
	global_load_dwordx4 v[230:233], v[252:253], off
	global_load_dwordx4 v[240:243], v[252:253], off offset:1024
	global_load_dwordx4 v[244:247], v[252:253], off offset:2048
	global_load_dwordx4 v[248:251], v[252:253], off offset:3072
	s_waitcnt vmcnt(0)
	v_mov_b32_e32 v70, v198
	v_mov_b32_e32 v71, v199
	v_mov_b32_e32 v72, v200
	v_mov_b32_e32 v73, v201
	v_mov_b32_e32 v74, v214
	v_mov_b32_e32 v75, v215
	v_mov_b32_e32 v76, v216
	v_mov_b32_e32 v77, v217
	v_mov_b32_e32 v78, v230
	v_mov_b32_e32 v79, v231
	v_mov_b32_e32 v80, v232
	v_mov_b32_e32 v81, v233
	v_mov_b32_e32 v87, v17
	v_mov_b32_e32 v68, v20
	v_mov_b32_e32 v69, v16
	v_pk_mul_f32 v[86:87], v[86:87], v[86:87]
	v_mov_b32_e32 v88, v22
	v_mov_b32_e32 v89, v18
	v_pk_fma_f32 v[68:69], v[68:69], v[68:69], v[86:87]
	v_mov_b32_e32 v90, v23
	v_pk_fma_f32 v[68:69], v[88:89], v[88:89], v[68:69]
	v_mov_b32_e32 v88, v13
	v_mov_b32_e32 v89, v9
	v_mov_b32_e32 v91, v19
	v_mov_b32_e32 v86, v12
	v_mov_b32_e32 v87, v8
	v_pk_mul_f32 v[88:89], v[88:89], v[88:89]
	v_pk_fma_f32 v[68:69], v[90:91], v[90:91], v[68:69]
	v_mov_b32_e32 v90, v14
	v_mov_b32_e32 v91, v10
	v_pk_fma_f32 v[86:87], v[86:87], v[86:87], v[88:89]
	v_mov_b32_e32 v92, v15
	v_mov_b32_e32 v93, v11
	v_pk_fma_f32 v[86:87], v[90:91], v[90:91], v[86:87]
	v_add_f32_e32 v31, v68, v69
	v_pk_fma_f32 v[86:87], v[92:93], v[92:93], v[86:87]
	v_lshlrev_b32_e32 v68, 2, v30
	v_add_f32_e32 v31, v31, v86
	v_add_f32_e32 v31, v31, v87
	ds_bpermute_b32 v33, v27, v31
	v_mov_b32_e32 v69, v165
	v_lshl_add_u64 v[86:87], v[82:83], 0, v[68:69]
	s_waitcnt lgkmcnt(0)
	v_add_f32_e32 v31, v31, v33
	ds_swizzle_b32 v33, v31 offset:swizzle(SWAP,16)
	s_waitcnt lgkmcnt(0)
	v_add_f32_e32 v31, v31, v33
	ds_swizzle_b32 v33, v31 offset:swizzle(SWAP,8)
	s_waitcnt lgkmcnt(0)
	v_add_f32_e32 v31, v31, v33
	ds_swizzle_b32 v33, v31 offset:swizzle(SWAP,4)
	s_waitcnt lgkmcnt(0)
	v_add_f32_e32 v31, v31, v33
	ds_swizzle_b32 v33, v31 offset:swizzle(SWAP,2)
	s_waitcnt lgkmcnt(0)
	v_add_f32_e32 v31, v31, v33
	ds_swizzle_b32 v33, v31 offset:swizzle(SWAP,1)
	s_waitcnt lgkmcnt(0)
	v_add_f32_e32 v31, v31, v33
	v_fmamk_f32 v31, v31, 0x3a800000, v189
	v_mul_f32_e32 v33, 0x4b800000, v31
	v_cmp_gt_f32_e32 vcc, s28, v31
	v_add_f32_e32 v35, 1.0, v79
	s_nop 0
	v_cndmask_b32_e32 v31, v31, v33, vcc
	v_rsq_f32_e32 v31, v31
	v_add_f32_e32 v41, 1.0, v80
	v_add_f32_e32 v51, 1.0, v81
	v_mul_f32_e32 v33, 0x45800000, v31
	v_cndmask_b32_e32 v31, v31, v33, vcc
	v_mul_f32_e32 v20, v20, v31
	v_mul_f32_e32 v21, v21, v31
	v_mul_f32_e32 v22, v22, v31
	v_mul_f32_e32 v23, v23, v31
	v_mul_f32_e32 v20, v70, v20
	v_mul_f32_e32 v21, v71, v21
	v_add_f32_e32 v33, 1.0, v78
	v_mul_f32_e32 v22, v72, v22
	v_mul_f32_e32 v23, v73, v23
	v_fma_f32 v20, v33, v20, v74
	v_fma_f32 v21, v35, v21, v75
	v_fma_f32 v22, v22, v41, v76
	v_fmac_f32_e32 v77, v23, v51
	v_cvt_pk_bf16_f32 v20, v20, v21
	v_cvt_pk_bf16_f32 v21, v22, v77
	global_store_dwordx2 v[38:39], v[20:21], off
	v_mov_b32_e32 v70, v202
	v_mov_b32_e32 v71, v203
	v_mov_b32_e32 v72, v204
	v_mov_b32_e32 v73, v205
	v_mov_b32_e32 v74, v240
	v_mov_b32_e32 v75, v241
	v_mov_b32_e32 v76, v242
	v_mov_b32_e32 v77, v243
	v_mov_b32_e32 v78, v218
	v_mov_b32_e32 v79, v219
	v_mov_b32_e32 v80, v220
	v_mov_b32_e32 v81, v221
	v_mul_f32_e32 v16, v16, v31
	v_mul_f32_e32 v17, v17, v31
	v_mul_f32_e32 v18, v18, v31
	v_mul_f32_e32 v19, v19, v31
	v_lshlrev_b32_e32 v20, 2, v32
	v_mov_b32_e32 v21, v165
	v_lshl_add_u64 v[22:23], v[82:83], 0, v[20:21]
	v_mul_f32_e32 v12, v12, v31
	v_mul_f32_e32 v13, v13, v31
	v_mul_f32_e32 v14, v14, v31
	v_mul_f32_e32 v15, v15, v31
	v_mul_f32_e32 v8, v8, v31
	v_mul_f32_e32 v9, v9, v31
	v_mul_f32_e32 v10, v10, v31
	v_mul_f32_e32 v11, v11, v31
	v_mul_f32_e32 v16, v16, v70
	v_add_f32_e32 v33, 1.0, v74
	v_mul_f32_e32 v17, v17, v71
	v_add_f32_e32 v35, 1.0, v75
	v_mul_f32_e32 v18, v18, v72
	v_add_f32_e32 v41, 1.0, v76
	v_mul_f32_e32 v19, v19, v73
	v_add_f32_e32 v51, 1.0, v77
	v_fma_f32 v16, v16, v33, v78
	v_fma_f32 v17, v17, v35, v79
	v_fma_f32 v18, v18, v41, v80
	v_fmac_f32_e32 v81, v19, v51
	v_cvt_pk_bf16_f32 v16, v16, v17
	v_cvt_pk_bf16_f32 v17, v18, v81
	global_store_dwordx2 v[38:39], v[16:17], off offset:512
	v_mov_b32_e32 v70, v206
	v_mov_b32_e32 v71, v207
	v_mov_b32_e32 v72, v208
	v_mov_b32_e32 v73, v209
	v_mov_b32_e32 v74, v244
	v_mov_b32_e32 v75, v245
	v_mov_b32_e32 v76, v246
	v_mov_b32_e32 v77, v247
	v_mov_b32_e32 v78, v222
	v_mov_b32_e32 v79, v223
	v_mov_b32_e32 v80, v224
	v_mov_b32_e32 v81, v225
	v_lshlrev_b32_e32 v16, 2, v34
	v_mov_b32_e32 v17, v165
	v_lshl_add_u64 v[18:19], v[82:83], 0, v[16:17]
	v_mul_f32_e32 v12, v12, v70
	v_add_f32_e32 v22, 1.0, v74
	v_mul_f32_e32 v13, v13, v71
	v_add_f32_e32 v23, 1.0, v75
	v_mul_f32_e32 v14, v14, v72
	v_add_f32_e32 v33, 1.0, v76
	v_mul_f32_e32 v15, v15, v73
	v_add_f32_e32 v35, 1.0, v77
	v_fma_f32 v12, v12, v22, v78
	v_fma_f32 v13, v13, v23, v79
	v_fma_f32 v14, v14, v33, v80
	v_fmac_f32_e32 v81, v15, v35
	v_cvt_pk_bf16_f32 v12, v12, v13
	v_cvt_pk_bf16_f32 v13, v14, v81
	global_store_dwordx2 v[38:39], v[12:13], off offset:1024
	v_mov_b32_e32 v12, v210
	v_mov_b32_e32 v13, v211
	v_mov_b32_e32 v14, v212
	v_mov_b32_e32 v15, v213
	s_nop 0
	v_mov_b32_e32 v70, v248
	v_mov_b32_e32 v71, v249
	v_mov_b32_e32 v72, v250
	v_mov_b32_e32 v73, v251
	v_mov_b32_e32 v74, v226
	v_mov_b32_e32 v75, v227
	v_mov_b32_e32 v76, v228
	v_mov_b32_e32 v77, v229
	v_mul_f32_e32 v8, v8, v12
	v_add_f32_e32 v12, 1.0, v70
	v_mul_f32_e32 v9, v9, v13
	v_add_f32_e32 v13, 1.0, v71
	v_mul_f32_e32 v10, v10, v14
	v_add_f32_e32 v14, 1.0, v72
	v_mul_f32_e32 v11, v11, v15
	v_add_f32_e32 v15, 1.0, v73
	v_fma_f32 v8, v8, v12, v74
	v_fma_f32 v9, v9, v13, v75
	v_fma_f32 v10, v10, v14, v76
	v_fmac_f32_e32 v77, v11, v15
	v_cvt_pk_bf16_f32 v8, v8, v9
	v_cvt_pk_bf16_f32 v9, v10, v77
	global_store_dwordx2 v[38:39], v[8:9], off offset:1536
	s_and_saveexec_b64 s[14:15], s[34:35]
	s_cbranch_execz .LBB0_148
	v_add_u32_e32 v8, 0xffffe000, v50
	v_lshrrev_b32_e32 v8, 12, v8
	v_add_u32_e32 v8, 1, v8
	v_cmp_lt_i32_e32 vcc, s48, v50
	v_mov_b64_e32 v[12:13], s[4:5]
	v_pk_mul_f32 v[60:61], v[60:61], v[60:61]
	v_cndmask_b32_e32 v8, 0, v8, vcc
	v_add_u32_e32 v14, s69, v8
	v_mad_u64_u32 v[18:19], s[6:7], v14, s50, v[12:13]
	v_lshl_add_u64 v[22:23], v[18:19], 0, s[58:59]
	v_lshl_add_u64 v[12:13], v[22:23], 0, v[164:165]
	v_lshl_add_u64 v[74:75], v[18:19], 0, v[164:165]
	v_pk_mul_f32 v[18:19], v[66:67], v[66:67]
	v_mov_b32_e32 v254, v12
	v_mov_b32_e32 v255, v13
	global_load_dwordx4 v[214:217], v[74:75], off
	global_load_dwordx4 v[218:221], v[74:75], off offset:1024
	global_load_dwordx4 v[222:225], v[74:75], off offset:2048
	global_load_dwordx4 v[226:229], v[74:75], off offset:3072
	global_load_dwordx4 v[230:233], v[254:255], off
	global_load_dwordx4 v[240:243], v[254:255], off offset:1024
	global_load_dwordx4 v[244:247], v[254:255], off offset:2048
	global_load_dwordx4 v[248:251], v[254:255], off offset:3072
	s_waitcnt vmcnt(0)
	v_mov_b32_e32 v8, v198
	v_mov_b32_e32 v9, v199
	v_mov_b32_e32 v10, v200
	v_mov_b32_e32 v11, v201
	v_mov_b32_e32 v12, v230
	v_mov_b32_e32 v13, v231
	v_mov_b32_e32 v14, v232
	v_mov_b32_e32 v15, v233
	v_mov_b32_e32 v70, v214
	v_mov_b32_e32 v71, v215
	v_mov_b32_e32 v72, v216
	v_mov_b32_e32 v73, v217
	v_pk_fma_f32 v[18:19], v[64:65], v[64:65], v[18:19]
	v_pk_fma_f32 v[56:57], v[56:57], v[56:57], v[60:61]
	v_pk_fma_f32 v[18:19], v[62:63], v[62:63], v[18:19]
	v_pk_fma_f32 v[54:55], v[54:55], v[54:55], v[56:57]
	v_pk_fma_f32 v[18:19], v[58:59], v[58:59], v[18:19]
	v_pk_fma_f32 v[52:53], v[52:53], v[52:53], v[54:55]
	v_add_f32_e32 v18, v18, v19
	v_add_f32_e32 v18, v53, v18
	v_add_f32_e32 v18, v52, v18
	ds_bpermute_b32 v19, v27, v18
	v_ashrrev_i32_e32 v51, 31, v50
	v_lshl_add_u64 v[16:17], v[22:23], 0, v[16:17]
	s_waitcnt lgkmcnt(0)
	v_add_f32_e32 v18, v18, v19
	ds_swizzle_b32 v19, v18 offset:swizzle(SWAP,16)
	s_waitcnt lgkmcnt(0)
	v_add_f32_e32 v18, v18, v19
	ds_swizzle_b32 v19, v18 offset:swizzle(SWAP,8)
	s_waitcnt lgkmcnt(0)
	v_add_f32_e32 v18, v18, v19
	ds_swizzle_b32 v19, v18 offset:swizzle(SWAP,4)
	s_waitcnt lgkmcnt(0)
	v_add_f32_e32 v18, v18, v19
	ds_swizzle_b32 v19, v18 offset:swizzle(SWAP,2)
	s_waitcnt lgkmcnt(0)
	v_add_f32_e32 v18, v18, v19
	ds_swizzle_b32 v19, v18 offset:swizzle(SWAP,1)
	s_waitcnt lgkmcnt(0)
	v_add_f32_e32 v18, v18, v19
	v_fmamk_f32 v18, v18, 0x3a800000, v189
	v_mul_f32_e32 v19, 0x4b800000, v18
	v_cmp_gt_f32_e32 vcc, s28, v18
	v_add_f32_e32 v12, 1.0, v12
	s_nop 0
	v_cndmask_b32_e32 v18, v18, v19, vcc
	v_rsq_f32_e32 v31, v18
	v_lshlrev_b64 v[18:19], 11, v[50:51]
	v_add_f32_e32 v13, 1.0, v13
	v_lshl_add_u64 v[54:55], v[36:37], 0, v[18:19]
	v_mul_f32_e32 v33, 0x45800000, v31
	v_cndmask_b32_e32 v31, v31, v33, vcc
	v_mul_f32_e32 v33, v49, v31
	v_mul_f32_e32 v35, v5, v31
	v_mul_f32_e32 v41, v47, v31
	v_mul_f32_e32 v50, v7, v31
	v_mul_f32_e32 v8, v8, v33
	v_mul_f32_e32 v9, v9, v35
	v_mul_f32_e32 v10, v10, v41
	v_mul_f32_e32 v11, v11, v50
	v_add_f32_e32 v14, 1.0, v14
	v_add_f32_e32 v15, 1.0, v15
	v_fma_f32 v8, v12, v8, v70
	v_fma_f32 v9, v13, v9, v71
	v_fma_f32 v10, v10, v14, v72
	v_fmac_f32_e32 v73, v11, v15
	v_cvt_pk_bf16_f32 v8, v8, v9
	v_cvt_pk_bf16_f32 v9, v10, v73
	global_store_dwordx2 v[54:55], v[8:9], off
	v_lshl_add_u64 v[18:19], v[22:23], 0, v[68:69]
	v_mov_b32_e32 v8, v202
	v_mov_b32_e32 v9, v203
	v_mov_b32_e32 v10, v204
	v_mov_b32_e32 v11, v205
	v_mov_b32_e32 v12, v240
	v_mov_b32_e32 v13, v241
	v_mov_b32_e32 v14, v242
	v_mov_b32_e32 v15, v243
	v_mov_b32_e32 v50, v218
	v_mov_b32_e32 v51, v219
	v_mov_b32_e32 v52, v220
	v_mov_b32_e32 v53, v221
	v_lshl_add_u64 v[18:19], v[22:23], 0, v[20:21]
	v_mul_f32_e32 v20, v48, v31
	v_mul_f32_e32 v21, v4, v31
	v_mul_f32_e32 v33, v46, v31
	v_mul_f32_e32 v35, v6, v31
	v_mul_f32_e32 v22, v45, v31
	v_mul_f32_e32 v23, v1, v31
	v_mul_f32_e32 v8, v20, v8
	v_add_f32_e32 v12, 1.0, v12
	v_mul_f32_e32 v9, v21, v9
	v_add_f32_e32 v13, 1.0, v13
	v_mul_f32_e32 v10, v33, v10
	v_add_f32_e32 v14, 1.0, v14
	v_mul_f32_e32 v11, v35, v11
	v_add_f32_e32 v15, 1.0, v15
	v_fma_f32 v8, v8, v12, v50
	v_fma_f32 v9, v9, v13, v51
	v_fma_f32 v10, v10, v14, v52
	v_fmac_f32_e32 v53, v11, v15
	v_cvt_pk_bf16_f32 v8, v8, v9
	v_cvt_pk_bf16_f32 v9, v10, v53
	global_store_dwordx2 v[54:55], v[8:9], off offset:512
	v_mov_b32_e32 v8, v206
	v_mov_b32_e32 v9, v207
	v_mov_b32_e32 v10, v208
	v_mov_b32_e32 v11, v209
	s_nop 0
	v_mov_b32_e32 v12, v244
	v_mov_b32_e32 v13, v245
	v_mov_b32_e32 v14, v246
	v_mov_b32_e32 v15, v247
	s_nop 0
	v_mov_b32_e32 v18, v222
	v_mov_b32_e32 v19, v223
	v_mov_b32_e32 v20, v224
	v_mov_b32_e32 v21, v225
	v_mul_f32_e32 v33, v43, v31
	v_mul_f32_e32 v35, v3, v31
	v_mul_f32_e32 v8, v22, v8
	v_add_f32_e32 v12, 1.0, v12
	v_mul_f32_e32 v9, v23, v9
	v_add_f32_e32 v13, 1.0, v13
	v_mul_f32_e32 v10, v33, v10
	v_add_f32_e32 v14, 1.0, v14
	v_mul_f32_e32 v11, v35, v11
	v_add_f32_e32 v15, 1.0, v15
	v_fma_f32 v8, v8, v12, v18
	v_fma_f32 v9, v9, v13, v19
	v_fma_f32 v10, v10, v14, v20
	v_fmac_f32_e32 v21, v11, v15
	v_cvt_pk_bf16_f32 v8, v8, v9
	v_cvt_pk_bf16_f32 v9, v10, v21
	global_store_dwordx2 v[54:55], v[8:9], off offset:1024
	v_mov_b32_e32 v8, v210
	v_mov_b32_e32 v9, v211
	v_mov_b32_e32 v10, v212
	v_mov_b32_e32 v11, v213
	s_nop 0
	v_mov_b32_e32 v12, v248
	v_mov_b32_e32 v13, v249
	v_mov_b32_e32 v14, v250
	v_mov_b32_e32 v15, v251
	s_nop 0
	v_mov_b32_e32 v16, v226
	v_mov_b32_e32 v17, v227
	v_mov_b32_e32 v18, v228
	v_mov_b32_e32 v19, v229
	v_mul_f32_e32 v20, v44, v31
	v_mul_f32_e32 v21, v0, v31
	v_mul_f32_e32 v22, v42, v31
	v_mul_f32_e32 v23, v2, v31
	v_mul_f32_e32 v8, v20, v8
	v_add_f32_e32 v12, 1.0, v12
	v_mul_f32_e32 v9, v21, v9
	v_add_f32_e32 v13, 1.0, v13
	v_mul_f32_e32 v10, v22, v10
	v_add_f32_e32 v14, 1.0, v14
	v_mul_f32_e32 v11, v23, v11
	v_add_f32_e32 v15, 1.0, v15
	v_fma_f32 v8, v8, v12, v16
	v_fma_f32 v9, v9, v13, v17
	v_fma_f32 v10, v10, v14, v18
	v_fmac_f32_e32 v19, v11, v15
	v_cvt_pk_bf16_f32 v8, v8, v9
	v_cvt_pk_bf16_f32 v9, v10, v19
	global_store_dwordx2 v[54:55], v[8:9], off offset:1536
	s_branch .LBB0_148

.LBB0_688:
	v_sub_f32_e32 v80, v80, v160
	v_exp_f32_e32 v80, v80
	v_sub_f32_e32 v81, v81, v160
	v_sub_f32_e32 v82, v82, v160
	v_exp_f32_e32 v81, v81
	v_sub_f32_e32 v64, v64, v160
	v_exp_f32_e32 v82, v82
	v_sub_f32_e32 v83, v83, v160
	v_exp_f32_e32 v97, v64
	v_sub_f32_e32 v64, v65, v160
	v_exp_f32_e32 v83, v83
	v_sub_f32_e32 v84, v84, v160
	v_exp_f32_e32 v98, v64
	v_sub_f32_e32 v64, v66, v160
	v_add_f32_e32 v96, 0, v80
	v_exp_f32_e32 v84, v84
	v_sub_f32_e32 v85, v85, v160
	v_exp_f32_e32 v99, v64
	v_sub_f32_e32 v64, v67, v160
	v_add_f32_e32 v96, v81, v96
	v_exp_f32_e32 v85, v85
	v_sub_f32_e32 v86, v86, v160
	v_exp_f32_e32 v100, v64
	v_sub_f32_e32 v64, v68, v160
	v_add_f32_e32 v96, v82, v96
	v_exp_f32_e32 v86, v86
	v_sub_f32_e32 v87, v87, v160
	v_exp_f32_e32 v101, v64
	v_sub_f32_e32 v64, v69, v160
	v_add_f32_e32 v96, v83, v96
	v_exp_f32_e32 v87, v87
	v_sub_f32_e32 v88, v88, v160
	v_exp_f32_e32 v102, v64
	v_sub_f32_e32 v64, v70, v160
	v_add_f32_e32 v96, v84, v96
	v_exp_f32_e32 v88, v88
	v_sub_f32_e32 v89, v89, v160
	v_exp_f32_e32 v103, v64
	v_sub_f32_e32 v64, v71, v160
	v_add_f32_e32 v96, v85, v96
	v_exp_f32_e32 v89, v89
	v_sub_f32_e32 v90, v90, v160
	v_exp_f32_e32 v104, v64
	v_sub_f32_e32 v64, v72, v160
	v_add_f32_e32 v96, v86, v96
	v_exp_f32_e32 v90, v90
	v_sub_f32_e32 v91, v91, v160
	v_exp_f32_e32 v72, v64
	v_sub_f32_e32 v64, v73, v160
	v_add_f32_e32 v96, v87, v96
	v_exp_f32_e32 v91, v91
	v_sub_f32_e32 v92, v92, v160
	v_exp_f32_e32 v73, v64
	v_sub_f32_e32 v64, v74, v160
	v_add_f32_e32 v96, v88, v96
	v_exp_f32_e32 v92, v92
	v_sub_f32_e32 v93, v93, v160
	v_exp_f32_e32 v74, v64
	v_sub_f32_e32 v64, v75, v160
	v_add_f32_e32 v96, v89, v96
	v_exp_f32_e32 v93, v93
	v_sub_f32_e32 v94, v94, v160
	v_exp_f32_e32 v75, v64
	v_sub_f32_e32 v64, v76, v160
	v_add_f32_e32 v96, v90, v96
	v_exp_f32_e32 v94, v94
	v_sub_f32_e32 v95, v95, v160
	v_exp_f32_e32 v76, v64
	v_sub_f32_e32 v64, v77, v160
	v_add_f32_e32 v96, v91, v96
	v_exp_f32_e32 v95, v95
	v_exp_f32_e32 v77, v64
	v_sub_f32_e32 v64, v78, v160
	v_add_f32_e32 v96, v92, v96
	v_exp_f32_e32 v78, v64
	v_sub_f32_e32 v64, v79, v160
	v_exp_f32_e32 v79, v64
	v_add_f32_e32 v64, v93, v96
	v_add_f32_e32 v64, v94, v64
	v_add_f32_e32 v96, v95, v64
	s_setprio 1
	v_cvt_pk_bf16_f32 v64, v80, v81
	v_add_u32_e32 v80, s6, v159
	ds_read_b128 v[68:71], v80 offset:24576
	v_cvt_pk_bf16_f32 v65, v82, v83
	v_cvt_pk_bf16_f32 v66, v84, v85
	v_cvt_pk_bf16_f32 v67, v86, v87
	s_waitcnt lgkmcnt(0)
	s_nop 0
	v_mfma_f32_32x32x16_bf16 v[48:63], v[68:71], v[64:67], v[48:63]
	ds_read_b128 v[68:71], v80 offset:28672
	s_waitcnt lgkmcnt(0)
	v_mfma_f32_32x32x16_bf16 v[32:47], v[68:71], v[64:67], v[32:47]
	ds_read_b128 v[68:71], v80 offset:32768
	s_waitcnt lgkmcnt(0)
	v_mfma_f32_32x32x16_bf16 v[16:31], v[68:71], v[64:67], v[16:31]
	ds_read_b128 v[68:71], v80 offset:36864
	v_add_u32_e32 v80, s6, v158
	s_waitcnt lgkmcnt(0)
	v_mfma_f32_32x32x16_bf16 v[0:15], v[68:71], v[64:67], v[0:15]
	ds_read_b128 v[68:71], v80 offset:24576
	v_cvt_pk_bf16_f32 v64, v88, v89
	v_cvt_pk_bf16_f32 v65, v90, v91
	v_cvt_pk_bf16_f32 v66, v92, v93
	v_cvt_pk_bf16_f32 v67, v94, v95
	s_waitcnt lgkmcnt(0)
	s_nop 0
	v_mfma_f32_32x32x16_bf16 v[48:63], v[68:71], v[64:67], v[48:63]
	ds_read_b128 v[68:71], v80 offset:28672
	s_waitcnt lgkmcnt(0)
	v_mfma_f32_32x32x16_bf16 v[32:47], v[68:71], v[64:67], v[32:47]
	ds_read_b128 v[68:71], v80 offset:32768
	s_waitcnt lgkmcnt(0)
	v_mfma_f32_32x32x16_bf16 v[16:31], v[68:71], v[64:67], v[16:31]
	ds_read_b128 v[68:71], v80 offset:36864
	v_add_u32_e32 v80, s6, v153
	s_waitcnt lgkmcnt(0)
	v_mfma_f32_32x32x16_bf16 v[0:15], v[68:71], v[64:67], v[0:15]
	ds_read_b128 v[68:71], v80 offset:24576
	v_cvt_pk_bf16_f32 v64, v97, v98
	v_cvt_pk_bf16_f32 v65, v99, v100
	v_cvt_pk_bf16_f32 v66, v101, v102
	v_cvt_pk_bf16_f32 v67, v103, v104
	s_waitcnt lgkmcnt(0)
	s_nop 0
	v_mfma_f32_32x32x16_bf16 v[48:63], v[68:71], v[64:67], v[48:63]
	ds_read_b128 v[68:71], v80 offset:28672
	s_waitcnt lgkmcnt(0)
	v_mfma_f32_32x32x16_bf16 v[32:47], v[68:71], v[64:67], v[32:47]
	ds_read_b128 v[68:71], v80 offset:32768
	s_waitcnt lgkmcnt(0)
	v_mfma_f32_32x32x16_bf16 v[16:31], v[68:71], v[64:67], v[16:31]
	ds_read_b128 v[68:71], v80 offset:36864
	v_add_u32_e32 v80, s6, v152
	s_waitcnt lgkmcnt(0)
	v_mfma_f32_32x32x16_bf16 v[0:15], v[68:71], v[64:67], v[0:15]
	ds_read_b128 v[68:71], v80 offset:24576
	v_cvt_pk_bf16_f32 v64, v72, v73
	v_cvt_pk_bf16_f32 v65, v74, v75
	v_cvt_pk_bf16_f32 v66, v76, v77
	v_cvt_pk_bf16_f32 v67, v78, v79
	s_waitcnt lgkmcnt(0)
	s_nop 0
	v_mfma_f32_32x32x16_bf16 v[48:63], v[68:71], v[64:67], v[48:63]
	ds_read_b128 v[68:71], v80 offset:28672
	s_waitcnt lgkmcnt(0)
	v_mfma_f32_32x32x16_bf16 v[32:47], v[68:71], v[64:67], v[32:47]
	ds_read_b128 v[68:71], v80 offset:32768
	s_waitcnt lgkmcnt(0)
	v_mfma_f32_32x32x16_bf16 v[16:31], v[68:71], v[64:67], v[16:31]
	ds_read_b128 v[68:71], v80 offset:36864
	s_waitcnt lgkmcnt(0)
	v_mfma_f32_32x32x16_bf16 v[0:15], v[68:71], v[64:67], v[0:15]
	v_add_f32_e32 v64, v97, v96
	v_add_f32_e32 v64, v98, v64
	v_add_f32_e32 v64, v99, v64
	v_add_f32_e32 v64, v100, v64
	v_add_f32_e32 v64, v101, v64
	v_add_f32_e32 v64, v102, v64
	v_add_f32_e32 v64, v103, v64
	v_add_f32_e32 v64, v104, v64
	v_add_f32_e32 v64, v72, v64
	v_add_f32_e32 v64, v73, v64
	v_add_f32_e32 v64, v74, v64
	v_add_f32_e32 v64, v75, v64
	v_add_f32_e32 v64, v76, v64
	v_add_f32_e32 v64, v77, v64
	v_add_f32_e32 v64, v78, v64
	v_add_f32_e32 v64, v79, v64
	v_add_f32_e32 v64, v147, v64
	s_setprio 0
	v_mov_b32_e32 v65, v64
	s_nop 1
	v_permlane32_swap_b32_e32 v64, v65
	v_add_f32_e32 v64, v64, v65
	v_div_scale_f32 v65, s[0:1], v64, v64, 1.0
	v_rcp_f32_e32 v66, v65
	s_lshl_b32 s0, s4, 7
	s_ashr_i32 s1, s0, 31
	v_mov_b32_e32 v147, v165
	v_fma_f32 v67, -v65, v66, 1.0
	v_fmac_f32_e32 v66, v67, v66
	v_div_scale_f32 v67, vcc, 1.0, v64, 1.0
	v_mul_f32_e32 v68, v67, v66
	v_fma_f32 v69, -v65, v68, v67
	v_fmac_f32_e32 v68, v69, v66
	v_fma_f32 v65, -v65, v68, v67
	v_div_fmas_f32 v65, v65, v66, v68
	v_div_fixup_f32 v66, v65, v64, 1.0
	v_lshlrev_b64 v[64:65], 11, v[144:145]
	v_lshl_add_u64 v[64:65], s[8:9], 0, v[64:65]
	v_lshl_add_u64 v[64:65], s[0:1], 1, v[64:65]
	v_mul_f32_e32 v48, v48, v66
	v_mul_f32_e32 v49, v49, v66
	v_mul_f32_e32 v50, v50, v66
	v_mul_f32_e32 v51, v51, v66
	v_cvt_pk_bf16_f32 v48, v48, v49
	v_cvt_pk_bf16_f32 v49, v50, v51
	v_lshl_add_u64 v[50:51], v[64:65], 0, v[146:147]
	s_mov_b64 s[0:1], 0x6078000
	v_lshl_add_u64 v[64:65], v[50:51], 0, s[0:1]
	s_mov_b32 s1, 0x6078000
	v_add_co_u32_e32 v50, vcc, s1, v50
	v_mul_f32_e32 v32, v32, v66
	v_mul_f32_e32 v33, v33, v66
	v_mul_f32_e32 v16, v16, v66
	v_mul_f32_e32 v17, v17, v66
	v_mul_f32_e32 v0, v0, v66
	v_mul_f32_e32 v1, v1, v66
	v_addc_co_u32_e32 v51, vcc, 0, v51, vcc
	v_mul_f32_e32 v34, v34, v66
	v_mul_f32_e32 v35, v35, v66
	v_cvt_pk_bf16_f32 v32, v32, v33
	v_cvt_pk_bf16_f32 v33, v34, v35
	v_mul_f32_e32 v18, v18, v66
	v_mul_f32_e32 v19, v19, v66
	v_cvt_pk_bf16_f32 v16, v16, v17
	v_cvt_pk_bf16_f32 v17, v18, v19
	v_mul_f32_e32 v2, v2, v66
	v_mul_f32_e32 v3, v3, v66
	v_cvt_pk_bf16_f32 v0, v0, v1
	v_cvt_pk_bf16_f32 v1, v2, v3
	s_waitcnt vmcnt(0)
	s_barrier
	global_store_dwordx2 v[50:51], v[48:49], off
	v_mul_f32_e32 v48, v52, v66
	v_mul_f32_e32 v49, v53, v66
	global_store_dwordx2 v[64:65], v[32:33], off offset:64
	v_mul_f32_e32 v32, v36, v66
	v_mul_f32_e32 v33, v37, v66
	global_store_dwordx2 v[64:65], v[16:17], off offset:128
	v_mul_f32_e32 v16, v20, v66
	v_mul_f32_e32 v17, v21, v66
	global_store_dwordx2 v[64:65], v[0:1], off offset:192
	v_mul_f32_e32 v0, v4, v66
	v_mul_f32_e32 v1, v5, v66
	v_mul_f32_e32 v50, v54, v66
	v_mul_f32_e32 v51, v55, v66
	v_cvt_pk_bf16_f32 v48, v48, v49
	v_cvt_pk_bf16_f32 v49, v50, v51
	v_mul_f32_e32 v34, v38, v66
	v_mul_f32_e32 v35, v39, v66
	v_cvt_pk_bf16_f32 v32, v32, v33
	v_cvt_pk_bf16_f32 v33, v34, v35
	v_mul_f32_e32 v18, v22, v66
	v_mul_f32_e32 v19, v23, v66
	v_cvt_pk_bf16_f32 v16, v16, v17
	v_cvt_pk_bf16_f32 v17, v18, v19
	v_mul_f32_e32 v2, v6, v66
	v_mul_f32_e32 v3, v7, v66
	v_cvt_pk_bf16_f32 v0, v0, v1
	v_cvt_pk_bf16_f32 v1, v2, v3
	global_store_dwordx2 v[64:65], v[48:49], off offset:16
	v_mul_f32_e32 v48, v56, v66
	v_mul_f32_e32 v49, v57, v66
	global_store_dwordx2 v[64:65], v[32:33], off offset:80
	v_mul_f32_e32 v32, v40, v66
	v_mul_f32_e32 v33, v41, v66
	global_store_dwordx2 v[64:65], v[16:17], off offset:144
	v_mul_f32_e32 v16, v24, v66
	v_mul_f32_e32 v17, v25, v66
	global_store_dwordx2 v[64:65], v[0:1], off offset:208
	v_mul_f32_e32 v0, v8, v66
	v_mul_f32_e32 v1, v9, v66
	v_mul_f32_e32 v50, v58, v66
	v_mul_f32_e32 v51, v59, v66
	v_cvt_pk_bf16_f32 v48, v48, v49
	v_cvt_pk_bf16_f32 v49, v50, v51
	v_mul_f32_e32 v34, v42, v66
	v_mul_f32_e32 v35, v43, v66
	v_cvt_pk_bf16_f32 v32, v32, v33
	v_cvt_pk_bf16_f32 v33, v34, v35
	v_mul_f32_e32 v18, v26, v66
	v_mul_f32_e32 v19, v27, v66
	v_cvt_pk_bf16_f32 v16, v16, v17
	v_cvt_pk_bf16_f32 v17, v18, v19
	v_mul_f32_e32 v2, v10, v66
	v_mul_f32_e32 v3, v11, v66
	v_cvt_pk_bf16_f32 v0, v0, v1
	v_cvt_pk_bf16_f32 v1, v2, v3
	s_mov_b32 s0, 0
	global_store_dwordx2 v[64:65], v[48:49], off offset:32
	v_mul_f32_e32 v48, v60, v66
	v_mul_f32_e32 v49, v61, v66
	global_store_dwordx2 v[64:65], v[32:33], off offset:96
	v_mul_f32_e32 v32, v44, v66
	v_mul_f32_e32 v33, v45, v66
	global_store_dwordx2 v[64:65], v[16:17], off offset:160
	v_mul_f32_e32 v16, v28, v66
	v_mul_f32_e32 v17, v29, v66
	global_store_dwordx2 v[64:65], v[0:1], off offset:224
	v_mul_f32_e32 v0, v12, v66
	v_mul_f32_e32 v1, v13, v66
	v_mul_f32_e32 v50, v62, v66
	v_mul_f32_e32 v51, v63, v66
	v_cvt_pk_bf16_f32 v48, v48, v49
	v_cvt_pk_bf16_f32 v49, v50, v51
	global_store_dwordx2 v[64:65], v[48:49], off offset:48
	v_mul_f32_e32 v34, v46, v66
	v_mul_f32_e32 v35, v47, v66
	v_cvt_pk_bf16_f32 v32, v32, v33
	v_cvt_pk_bf16_f32 v33, v34, v35
	global_store_dwordx2 v[64:65], v[32:33], off offset:112
	v_mul_f32_e32 v18, v30, v66
	v_mul_f32_e32 v19, v31, v66
	v_cvt_pk_bf16_f32 v16, v16, v17
	v_cvt_pk_bf16_f32 v17, v18, v19
	global_store_dwordx2 v[64:65], v[16:17], off offset:176
	v_mul_f32_e32 v2, v14, v66
	v_mul_f32_e32 v3, v15, v66
	v_cvt_pk_bf16_f32 v0, v0, v1
	v_cvt_pk_bf16_f32 v1, v2, v3
	global_store_dwordx2 v[64:65], v[0:1], off offset:240

.LBB0_1404:
	s_add_u32 s16, s10, 0xfffc0080
	s_addc_u32 s17, s11, -1
	s_add_i32 s41, 0, 0x10000
	v_add_u32_e32 v132, s41, v198
	ds_read_b128 v[116:119], v132
	ds_read_b128 v[124:127], v132 offset:1024
	ds_read_b128 v[128:131], v132 offset:2048
	ds_read_b128 v[132:135], v132 offset:3072
	s_cmp_eq_u32 s40, 12
	s_cselect_b32 s35, s6, s17
	s_cselect_b32 s34, s31, s16
	s_cselect_b32 s17, s5, s39
	s_cselect_b32 s16, s36, s37
	v_lshl_add_u64 v[186:187], s[10:11], 0, v[176:177]
	s_add_i32 m0, s33, 0xc000
	ds_read_b128 v[136:139], v199
	ds_read_b128 v[140:143], v199 offset:1024
	ds_read_b128 v[144:147], v199 offset:2048
	ds_read_b128 v[148:151], v199 offset:3072
	ds_read_b128 v[152:155], v199 offset:4096
	ds_read_b128 v[178:181], v199 offset:5120
	ds_read_b128 v[182:185], v199 offset:6144
	ds_read_b128 v[200:203], v199 offset:7168
	global_load_lds_dwordx4 v[186:187], off
	v_lshl_add_u64 v[186:187], s[10:11], 0, v[174:175]
	s_add_i32 m0, s33, 0xe000
	s_nop 0
	global_load_lds_dwordx4 v[186:187], off
	s_waitcnt lgkmcnt(8)
	s_barrier
	s_waitcnt lgkmcnt(0)
	s_setprio 1
	s_waitcnt lgkmcnt(0)
	v_mfma_f32_16x16x32_bf16 v[160:163], v[116:119], v[136:139], v[160:163]
	v_mfma_f32_16x16x32_bf16 v[60:63], v[128:131], v[136:139], v[60:63]
	v_mfma_f32_16x16x32_bf16 v[120:123], v[116:119], v[144:147], v[120:123]
	v_mfma_f32_16x16x32_bf16 v[52:55], v[128:131], v[144:147], v[52:55]
	v_mfma_f32_16x16x32_bf16 v[108:111], v[116:119], v[152:155], v[108:111]
	v_mfma_f32_16x16x32_bf16 v[44:47], v[128:131], v[152:155], v[44:47]
	v_mfma_f32_16x16x32_bf16 v[100:103], v[116:119], v[182:185], v[100:103]
	v_mfma_f32_16x16x32_bf16 v[36:39], v[128:131], v[182:185], v[36:39]
	v_mfma_f32_16x16x32_bf16 v[160:163], v[124:127], v[140:143], v[160:163]
	v_mfma_f32_16x16x32_bf16 v[60:63], v[132:135], v[140:143], v[60:63]
	v_mfma_f32_16x16x32_bf16 v[120:123], v[124:127], v[148:151], v[120:123]
	v_mfma_f32_16x16x32_bf16 v[52:55], v[132:135], v[148:151], v[52:55]
	v_mfma_f32_16x16x32_bf16 v[108:111], v[124:127], v[178:181], v[108:111]
	v_mfma_f32_16x16x32_bf16 v[44:47], v[132:135], v[178:181], v[44:47]
	v_mfma_f32_16x16x32_bf16 v[100:103], v[124:127], v[200:203], v[100:103]
	v_mfma_f32_16x16x32_bf16 v[36:39], v[132:135], v[200:203], v[36:39]
	s_setprio 0
	s_barrier
	s_add_i32 s48, 0, 0x14000
	s_add_i32 s41, s41, s27
	v_add_u32_e32 v164, s48, v198
	v_lshl_add_u64 v[186:187], s[16:17], 0, v[172:173]
	s_mov_b32 m0, s41
	ds_read_b128 v[204:207], v164
	ds_read_b128 v[208:211], v164 offset:1024
	ds_read_b128 v[212:215], v164 offset:2048
	ds_read_b128 v[216:219], v164 offset:3072
	global_load_lds_dwordx4 v[186:187], off
	v_lshl_add_u64 v[186:187], s[16:17], 0, v[168:169]
	s_add_i32 m0, s41, 0x2000
	s_nop 0
	global_load_lds_dwordx4 v[186:187], off
	s_barrier
	s_waitcnt lgkmcnt(0)
	s_setprio 1
	s_waitcnt lgkmcnt(0)
	v_mfma_f32_16x16x32_bf16 v[156:159], v[204:207], v[136:139], v[156:159]
	v_mfma_f32_16x16x32_bf16 v[56:59], v[212:215], v[136:139], v[56:59]
	v_mfma_f32_16x16x32_bf16 v[112:115], v[204:207], v[144:147], v[112:115]
	v_mfma_f32_16x16x32_bf16 v[48:51], v[212:215], v[144:147], v[48:51]
	v_mfma_f32_16x16x32_bf16 v[104:107], v[204:207], v[152:155], v[104:107]
	v_mfma_f32_16x16x32_bf16 v[40:43], v[212:215], v[152:155], v[40:43]
	v_mfma_f32_16x16x32_bf16 v[96:99], v[204:207], v[182:185], v[96:99]
	v_mfma_f32_16x16x32_bf16 v[32:35], v[212:215], v[182:185], v[32:35]
	v_mfma_f32_16x16x32_bf16 v[156:159], v[208:211], v[140:143], v[156:159]
	v_mfma_f32_16x16x32_bf16 v[56:59], v[216:219], v[140:143], v[56:59]
	v_mfma_f32_16x16x32_bf16 v[112:115], v[208:211], v[148:151], v[112:115]
	v_mfma_f32_16x16x32_bf16 v[48:51], v[216:219], v[148:151], v[48:51]
	v_mfma_f32_16x16x32_bf16 v[104:107], v[208:211], v[178:181], v[104:107]
	v_mfma_f32_16x16x32_bf16 v[40:43], v[216:219], v[178:181], v[40:43]
	v_mfma_f32_16x16x32_bf16 v[96:99], v[208:211], v[200:203], v[96:99]
	v_mfma_f32_16x16x32_bf16 v[32:35], v[216:219], v[200:203], v[32:35]
	s_setprio 0
	s_mov_b32 m0, s33
	v_lshl_add_u64 v[186:187], s[34:35], 0, v[170:171]
	s_barrier
	ds_read_b128 v[136:139], v199 offset:16384
	ds_read_b128 v[140:143], v199 offset:17408
	ds_read_b128 v[144:147], v199 offset:18432
	ds_read_b128 v[148:151], v199 offset:19456
	ds_read_b128 v[152:155], v199 offset:20480
	ds_read_b128 v[178:181], v199 offset:21504
	ds_read_b128 v[182:185], v199 offset:22528
	ds_read_b128 v[200:203], v199 offset:23552
	global_load_lds_dwordx4 v[186:187], off
	v_lshl_add_u64 v[220:221], s[34:35], 0, v[166:167]
	s_mov_b32 m0, s2
	s_nop 0
	global_load_lds_dwordx4 v[220:221], off
	s_barrier
	s_waitcnt lgkmcnt(0)
	s_setprio 1
	s_waitcnt lgkmcnt(0)
	v_mfma_f32_16x16x32_bf16 v[92:95], v[116:119], v[136:139], v[92:95]
	v_mfma_f32_16x16x32_bf16 v[28:31], v[128:131], v[136:139], v[28:31]
	v_mfma_f32_16x16x32_bf16 v[84:87], v[116:119], v[144:147], v[84:87]
	v_mfma_f32_16x16x32_bf16 v[20:23], v[128:131], v[144:147], v[20:23]
	v_mfma_f32_16x16x32_bf16 v[76:79], v[116:119], v[152:155], v[76:79]
	v_mfma_f32_16x16x32_bf16 v[12:15], v[128:131], v[152:155], v[12:15]
	v_mfma_f32_16x16x32_bf16 v[68:71], v[116:119], v[182:185], v[68:71]
	v_mfma_f32_16x16x32_bf16 v[4:7], v[128:131], v[182:185], v[4:7]
	v_mfma_f32_16x16x32_bf16 v[92:95], v[124:127], v[140:143], v[92:95]
	v_mfma_f32_16x16x32_bf16 v[28:31], v[132:135], v[140:143], v[28:31]
	v_mfma_f32_16x16x32_bf16 v[84:87], v[124:127], v[148:151], v[84:87]
	v_mfma_f32_16x16x32_bf16 v[20:23], v[132:135], v[148:151], v[20:23]
	v_mfma_f32_16x16x32_bf16 v[76:79], v[124:127], v[178:181], v[76:79]
	v_mfma_f32_16x16x32_bf16 v[12:15], v[132:135], v[178:181], v[12:15]
	v_mfma_f32_16x16x32_bf16 v[68:71], v[124:127], v[200:203], v[68:71]
	v_mfma_f32_16x16x32_bf16 v[4:7], v[132:135], v[200:203], v[4:7]
	s_setprio 0
	s_barrier
	s_add_u32 s52, s16, 0x4000
	s_addc_u32 s53, s17, 0
	s_add_i32 s41, s48, s27
	v_lshl_add_u64 v[116:117], s[52:53], 0, v[172:173]
	s_mov_b32 m0, s41
	s_nop 0
	global_load_lds_dwordx4 v[116:117], off
	v_lshl_add_u64 v[116:117], s[52:53], 0, v[168:169]
	s_add_i32 m0, s41, 0x2000
	s_nop 0
	global_load_lds_dwordx4 v[116:117], off
	s_waitcnt vmcnt(6)
	s_barrier
	s_setprio 1
	v_mfma_f32_16x16x32_bf16 v[88:91], v[204:207], v[136:139], v[88:91]
	v_mfma_f32_16x16x32_bf16 v[24:27], v[212:215], v[136:139], v[24:27]
	v_mfma_f32_16x16x32_bf16 v[80:83], v[204:207], v[144:147], v[80:83]
	v_mfma_f32_16x16x32_bf16 v[16:19], v[212:215], v[144:147], v[16:19]
	v_mfma_f32_16x16x32_bf16 v[72:75], v[204:207], v[152:155], v[72:75]
	v_mfma_f32_16x16x32_bf16 v[8:11], v[212:215], v[152:155], v[8:11]
	v_mfma_f32_16x16x32_bf16 v[64:67], v[204:207], v[182:185], v[64:67]
	v_mfma_f32_16x16x32_bf16 v[0:3], v[212:215], v[182:185], v[0:3]
	v_mfma_f32_16x16x32_bf16 v[88:91], v[208:211], v[140:143], v[88:91]
	v_mfma_f32_16x16x32_bf16 v[24:27], v[216:219], v[140:143], v[24:27]
	v_mfma_f32_16x16x32_bf16 v[80:83], v[208:211], v[148:151], v[80:83]
	v_mfma_f32_16x16x32_bf16 v[16:19], v[216:219], v[148:151], v[16:19]
	v_mfma_f32_16x16x32_bf16 v[72:75], v[208:211], v[178:181], v[72:75]
	v_mfma_f32_16x16x32_bf16 v[8:11], v[216:219], v[178:181], v[8:11]
	v_mfma_f32_16x16x32_bf16 v[64:67], v[208:211], v[200:203], v[64:67]
	v_mfma_f32_16x16x32_bf16 v[0:3], v[216:219], v[200:203], v[0:3]
	s_setprio 0
	s_add_i32 s41, 0, 0x18000
	v_add_u32_e32 v132, s41, v198
	s_barrier
	ds_read_b128 v[116:119], v132
	ds_read_b128 v[124:127], v132 offset:1024
	ds_read_b128 v[128:131], v132 offset:2048
	ds_read_b128 v[132:135], v132 offset:3072
	s_add_u32 s34, s34, 0x40000
	s_addc_u32 s35, s35, 0
	s_mov_b32 m0, s78
	v_lshl_add_u64 v[204:205], s[34:35], 0, v[170:171]
	ds_read_b128 v[136:139], v199 offset:32768
	ds_read_b128 v[140:143], v199 offset:33792
	ds_read_b128 v[144:147], v199 offset:34816
	ds_read_b128 v[148:151], v199 offset:35840
	ds_read_b128 v[152:155], v199 offset:36864
	ds_read_b128 v[178:181], v199 offset:37888
	ds_read_b128 v[182:185], v199 offset:38912
	ds_read_b128 v[200:203], v199 offset:39936
	global_load_lds_dwordx4 v[204:205], off
	v_lshl_add_u64 v[204:205], s[34:35], 0, v[166:167]
	s_mov_b32 m0, s79
	s_nop 0
	global_load_lds_dwordx4 v[204:205], off
	s_waitcnt lgkmcnt(8)
	s_barrier
	s_waitcnt lgkmcnt(0)
	s_setprio 1
	s_waitcnt lgkmcnt(0)
	v_mfma_f32_16x16x32_bf16 v[160:163], v[116:119], v[136:139], v[160:163]
	v_mfma_f32_16x16x32_bf16 v[60:63], v[128:131], v[136:139], v[60:63]
	v_mfma_f32_16x16x32_bf16 v[120:123], v[116:119], v[144:147], v[120:123]
	v_mfma_f32_16x16x32_bf16 v[52:55], v[128:131], v[144:147], v[52:55]
	v_mfma_f32_16x16x32_bf16 v[108:111], v[116:119], v[152:155], v[108:111]
	v_mfma_f32_16x16x32_bf16 v[44:47], v[128:131], v[152:155], v[44:47]
	v_mfma_f32_16x16x32_bf16 v[100:103], v[116:119], v[182:185], v[100:103]
	v_mfma_f32_16x16x32_bf16 v[36:39], v[128:131], v[182:185], v[36:39]
	v_mfma_f32_16x16x32_bf16 v[160:163], v[124:127], v[140:143], v[160:163]
	v_mfma_f32_16x16x32_bf16 v[60:63], v[132:135], v[140:143], v[60:63]
	v_mfma_f32_16x16x32_bf16 v[120:123], v[124:127], v[148:151], v[120:123]
	v_mfma_f32_16x16x32_bf16 v[52:55], v[132:135], v[148:151], v[52:55]
	v_mfma_f32_16x16x32_bf16 v[108:111], v[124:127], v[178:181], v[108:111]
	v_mfma_f32_16x16x32_bf16 v[44:47], v[132:135], v[178:181], v[44:47]
	v_mfma_f32_16x16x32_bf16 v[100:103], v[124:127], v[200:203], v[100:103]
	v_mfma_f32_16x16x32_bf16 v[36:39], v[132:135], v[200:203], v[36:39]
	s_setprio 0
	s_barrier
	s_add_i32 s48, 0, 0x1c000
	s_add_u32 s34, s16, 0x8000
	s_addc_u32 s35, s17, 0
	s_add_i32 s41, s41, s27
	v_add_u32_e32 v164, s48, v198
	v_lshl_add_u64 v[222:223], s[34:35], 0, v[172:173]
	s_mov_b32 m0, s41
	ds_read_b128 v[204:207], v164
	ds_read_b128 v[208:211], v164 offset:1024
	ds_read_b128 v[212:215], v164 offset:2048
	ds_read_b128 v[216:219], v164 offset:3072
	global_load_lds_dwordx4 v[222:223], off
	v_lshl_add_u64 v[222:223], s[34:35], 0, v[168:169]
	s_add_i32 m0, s41, 0x2000
	s_nop 0
	global_load_lds_dwordx4 v[222:223], off
	s_barrier
	s_waitcnt lgkmcnt(0)
	s_setprio 1
	s_waitcnt lgkmcnt(0)
	v_mfma_f32_16x16x32_bf16 v[156:159], v[204:207], v[136:139], v[156:159]
	v_mfma_f32_16x16x32_bf16 v[56:59], v[212:215], v[136:139], v[56:59]
	v_mfma_f32_16x16x32_bf16 v[112:115], v[204:207], v[144:147], v[112:115]
	v_mfma_f32_16x16x32_bf16 v[48:51], v[212:215], v[144:147], v[48:51]
	v_mfma_f32_16x16x32_bf16 v[104:107], v[204:207], v[152:155], v[104:107]
	v_mfma_f32_16x16x32_bf16 v[40:43], v[212:215], v[152:155], v[40:43]
	v_mfma_f32_16x16x32_bf16 v[96:99], v[204:207], v[182:185], v[96:99]
	v_mfma_f32_16x16x32_bf16 v[32:35], v[212:215], v[182:185], v[32:35]
	v_mfma_f32_16x16x32_bf16 v[156:159], v[208:211], v[140:143], v[156:159]
	v_mfma_f32_16x16x32_bf16 v[56:59], v[216:219], v[140:143], v[56:59]
	v_mfma_f32_16x16x32_bf16 v[112:115], v[208:211], v[148:151], v[112:115]
	v_mfma_f32_16x16x32_bf16 v[48:51], v[216:219], v[148:151], v[48:51]
	v_mfma_f32_16x16x32_bf16 v[104:107], v[208:211], v[178:181], v[104:107]
	v_mfma_f32_16x16x32_bf16 v[40:43], v[216:219], v[178:181], v[40:43]
	v_mfma_f32_16x16x32_bf16 v[96:99], v[208:211], v[200:203], v[96:99]
	v_mfma_f32_16x16x32_bf16 v[32:35], v[216:219], v[200:203], v[32:35]
	s_setprio 0
	s_mov_b32 m0, s82
	v_lshl_add_u64 v[186:187], v[186:187], 0, s[18:19]
	s_barrier
	ds_read_b128 v[136:139], v199 offset:49152
	ds_read_b128 v[140:143], v199 offset:50176
	ds_read_b128 v[144:147], v199 offset:51200
	ds_read_b128 v[148:151], v199 offset:52224
	ds_read_b128 v[152:155], v199 offset:53248
	ds_read_b128 v[178:181], v199 offset:54272
	ds_read_b128 v[182:185], v199 offset:55296
	ds_read_b128 v[200:203], v199 offset:56320
	global_load_lds_dwordx4 v[186:187], off
	v_lshl_add_u64 v[186:187], v[220:221], 0, s[18:19]
	s_mov_b32 m0, s83
	s_nop 0
	global_load_lds_dwordx4 v[186:187], off
	s_barrier
	s_waitcnt lgkmcnt(0)
	s_setprio 1
	s_waitcnt lgkmcnt(0)
	v_mfma_f32_16x16x32_bf16 v[92:95], v[116:119], v[136:139], v[92:95]
	v_mfma_f32_16x16x32_bf16 v[28:31], v[128:131], v[136:139], v[28:31]
	v_mfma_f32_16x16x32_bf16 v[84:87], v[116:119], v[144:147], v[84:87]
	v_mfma_f32_16x16x32_bf16 v[20:23], v[128:131], v[144:147], v[20:23]
	v_mfma_f32_16x16x32_bf16 v[76:79], v[116:119], v[152:155], v[76:79]
	v_mfma_f32_16x16x32_bf16 v[12:15], v[128:131], v[152:155], v[12:15]
	v_mfma_f32_16x16x32_bf16 v[68:71], v[116:119], v[182:185], v[68:71]
	v_mfma_f32_16x16x32_bf16 v[4:7], v[128:131], v[182:185], v[4:7]
	v_mfma_f32_16x16x32_bf16 v[92:95], v[124:127], v[140:143], v[92:95]
	v_mfma_f32_16x16x32_bf16 v[28:31], v[132:135], v[140:143], v[28:31]
	v_mfma_f32_16x16x32_bf16 v[84:87], v[124:127], v[148:151], v[84:87]
	v_mfma_f32_16x16x32_bf16 v[20:23], v[132:135], v[148:151], v[20:23]
	v_mfma_f32_16x16x32_bf16 v[76:79], v[124:127], v[178:181], v[76:79]
	v_mfma_f32_16x16x32_bf16 v[12:15], v[132:135], v[178:181], v[12:15]
	v_mfma_f32_16x16x32_bf16 v[68:71], v[124:127], v[200:203], v[68:71]
	v_mfma_f32_16x16x32_bf16 v[4:7], v[132:135], v[200:203], v[4:7]
	s_setprio 0
	s_barrier
	s_add_u32 s16, s16, 0xc000
	s_addc_u32 s17, s17, 0
	s_add_i32 s34, s48, s27
	v_lshl_add_u64 v[116:117], s[16:17], 0, v[172:173]
	s_mov_b32 m0, s34
	s_nop 0
	global_load_lds_dwordx4 v[116:117], off
	v_lshl_add_u64 v[116:117], s[16:17], 0, v[168:169]
	s_add_i32 m0, s34, 0x2000
	s_nop 0
	global_load_lds_dwordx4 v[116:117], off
	s_waitcnt vmcnt(6)
	s_barrier
	s_setprio 1
	v_mfma_f32_16x16x32_bf16 v[88:91], v[204:207], v[136:139], v[88:91]
	v_mfma_f32_16x16x32_bf16 v[24:27], v[212:215], v[136:139], v[24:27]
	v_mfma_f32_16x16x32_bf16 v[80:83], v[204:207], v[144:147], v[80:83]
	v_mfma_f32_16x16x32_bf16 v[16:19], v[212:215], v[144:147], v[16:19]
	v_mfma_f32_16x16x32_bf16 v[72:75], v[204:207], v[152:155], v[72:75]
	v_mfma_f32_16x16x32_bf16 v[8:11], v[212:215], v[152:155], v[8:11]
	v_mfma_f32_16x16x32_bf16 v[64:67], v[204:207], v[182:185], v[64:67]
	v_mfma_f32_16x16x32_bf16 v[0:3], v[212:215], v[182:185], v[0:3]
	v_mfma_f32_16x16x32_bf16 v[88:91], v[208:211], v[140:143], v[88:91]
	v_mfma_f32_16x16x32_bf16 v[24:27], v[216:219], v[140:143], v[24:27]
	v_mfma_f32_16x16x32_bf16 v[80:83], v[208:211], v[148:151], v[80:83]
	v_mfma_f32_16x16x32_bf16 v[16:19], v[216:219], v[148:151], v[16:19]
	v_mfma_f32_16x16x32_bf16 v[72:75], v[208:211], v[178:181], v[72:75]
	v_mfma_f32_16x16x32_bf16 v[8:11], v[216:219], v[178:181], v[8:11]
	v_mfma_f32_16x16x32_bf16 v[64:67], v[208:211], v[200:203], v[64:67]
	v_mfma_f32_16x16x32_bf16 v[0:3], v[216:219], v[200:203], v[0:3]
	s_setprio 0
	s_add_i32 s40, s40, 2
	s_add_u32 s37, s37, 0x10000
	s_addc_u32 s39, s39, 0
	s_add_u32 s10, s10, 0x100
	s_addc_u32 s11, s11, 0
	s_cmp_gt_u32 s40, 13
	s_barrier
	s_cbranch_scc0 .LBB0_1404
	v_mov_b32_e32 v116, v188
	s_lshl_b32 s6, s38, 7
	v_readfirstlane_b32 s10, v116
	s_lshr_b32 s5, s10, 1
	v_and_b32_e32 v200, 15, v116
	s_and_b32 s5, s5, 0x60
	v_lshrrev_b32_e32 v116, 1, v116
	s_or_b32 s6, s5, s6
	v_and_b32_e32 v116, 24, v116
	v_or_b32_e32 v182, s6, v116
	v_ashrrev_i32_e32 v183, 31, v182
	v_lshlrev_b64 v[118:119], 2, v[182:183]
	v_lshl_add_u64 v[184:185], s[42:43], 0, v[118:119]
	global_load_dwordx4 v[124:127], v[184:185], off
	v_lshl_add_u64 v[128:129], s[58:59], 0, v[118:119]
	global_load_dwordx4 v[128:131], v[128:129], off
	v_lshl_add_u64 v[132:133], s[60:61], 0, v[118:119]
	global_load_dwordx4 v[132:135], v[132:133], off
	v_lshl_add_u64 v[186:187], s[46:47], 0, v[118:119]
	global_load_dwordx4 v[136:139], v[186:187], off
	v_lshl_add_u64 v[140:141], s[12:13], 0, v[118:119]
	global_load_dwordx4 v[140:143], v[140:141], off
	v_lshl_add_u64 v[144:145], s[50:51], 0, v[118:119]
	global_load_dwordx4 v[144:147], v[144:145], off
	v_lshl_add_u64 v[148:149], s[20:21], 0, v[118:119]
	global_load_dwordx4 v[148:151], v[148:149], off
	v_lshl_add_u64 v[118:119], s[44:45], 0, v[118:119]
	global_load_dwordx4 v[152:155], v[118:119], off
	v_cmp_eq_u32_e32 vcc, 15, v200
	v_cmp_eq_u32_e64 s[34:35], 0, v200
	s_nop 0
	v_cndmask_b32_e64 v117, v160, 0, vcc
	v_cndmask_b32_e64 v118, v160, v120, s[34:35]
	v_cndmask_b32_e64 v164, v156, v112, s[34:35]
	s_nop 0
	v_mov_b32_dpp v119, v118 row_ror:15 row_mask:0xf bank_mask:0xf
	v_cndmask_b32_e64 v118, v156, 0, vcc
	v_mov_b32_dpp v178, v164 row_ror:15 row_mask:0xf bank_mask:0xf
	v_mov_b32_e32 v180, v165
	s_lshl_b32 s11, s7, 8
	s_ashr_i32 s7, s10, 2
	s_andn2_b32 s7, s7, 63
	s_add_i32 s31, s7, s11
	v_mov_b32_e32 v181, v165
	s_ashr_i32 s10, s31, 6
	s_ashr_i32 s11, s10, 31
	s_lshl_b32 s16, s38, 8
	s_lshl_b64 s[52:53], s[10:11], 2
	v_cmp_gt_u32_e64 s[36:37], 2, v200
	s_ashr_i32 s17, s16, 31
	v_or_b32_e32 v183, s52, v200
	s_waitcnt vmcnt(0)
	v_mul_f32_dpp v117, v117, v124 row_ror:1 row_mask:0xf bank_mask:0xf bound_ctrl:1
	v_fmac_f32_e32 v117, v160, v128
	v_fmac_f32_e32 v117, v132, v119
	v_add_f32_e32 v117, v136, v117
	v_mul_f32_e32 v119, 0xbfb8aa3b, v117
	v_exp_f32_e32 v119, v119
	v_mul_f32_dpp v118, v118, v140 row_ror:1 row_mask:0xf bank_mask:0xf bound_ctrl:1
	v_fmac_f32_e32 v118, v156, v144
	v_add_f32_e32 v119, 1.0, v119
	v_rcp_f32_e32 v119, v119
	v_fmac_f32_e32 v118, v148, v178
	v_add_f32_e32 v118, v152, v118
	v_cndmask_b32_e64 v178, v157, v113, s[34:35]
	v_mul_f32_e32 v117, v117, v119
	v_mul_f32_e32 v117, v118, v117
	v_cndmask_b32_e64 v118, v161, 0, vcc
	v_cndmask_b32_e64 v119, v161, v121, s[34:35]
	v_mov_b32_dpp v179, v178 row_ror:15 row_mask:0xf bank_mask:0xf
	v_mul_f32_dpp v118, v118, v125 row_ror:1 row_mask:0xf bank_mask:0xf bound_ctrl:1
	v_fmac_f32_e32 v118, v161, v129
	v_fmac_f32_dpp v118, v119, v133 row_ror:15 row_mask:0xf bank_mask:0xf
	v_add_f32_e32 v118, v137, v118
	v_mul_f32_e32 v164, 0xbfb8aa3b, v118
	v_exp_f32_e32 v164, v164
	v_cndmask_b32_e64 v119, v157, 0, vcc
	v_add_f32_e32 v164, 1.0, v164
	v_rcp_f32_e32 v164, v164
	v_mul_f32_dpp v119, v119, v141 row_ror:1 row_mask:0xf bank_mask:0xf bound_ctrl:1
	v_fmac_f32_e32 v119, v157, v145
	v_fmac_f32_e32 v119, v149, v179
	v_add_f32_e32 v119, v153, v119
	v_mul_f32_e32 v118, v118, v164
	v_mul_f32_e32 v118, v119, v118
	v_cndmask_b32_e64 v119, v162, 0, vcc
	v_cndmask_b32_e64 v164, v162, v122, s[34:35]
	v_cndmask_b32_e64 v179, v158, v114, s[34:35]
	v_mul_f32_dpp v119, v119, v126 row_ror:1 row_mask:0xf bank_mask:0xf bound_ctrl:1
	v_fmac_f32_e32 v119, v162, v130
	v_fmac_f32_dpp v119, v164, v134 row_ror:15 row_mask:0xf bank_mask:0xf
	v_add_f32_e32 v119, v138, v119
	v_mul_f32_e32 v178, 0xbfb8aa3b, v119
	v_exp_f32_e32 v178, v178
	v_cndmask_b32_e64 v164, v158, 0, vcc
	v_mov_b32_dpp v180, v179 row_ror:15 row_mask:0xf bank_mask:0xf
	v_add_f32_e32 v178, 1.0, v178
	v_rcp_f32_e32 v178, v178
	v_mul_f32_dpp v164, v164, v142 row_ror:1 row_mask:0xf bank_mask:0xf bound_ctrl:1
	v_fmac_f32_e32 v164, v158, v146
	v_fmac_f32_e32 v164, v150, v180
	v_add_f32_e32 v164, v154, v164
	v_mul_f32_e32 v119, v119, v178
	v_mul_f32_e32 v119, v164, v119
	v_cndmask_b32_e64 v164, v163, 0, vcc
	v_cndmask_b32_e64 v178, v163, v123, s[34:35]
	v_cndmask_b32_e64 v180, v159, v115, s[34:35]
	v_mul_f32_dpp v164, v164, v127 row_ror:1 row_mask:0xf bank_mask:0xf bound_ctrl:1
	v_fmac_f32_e32 v164, v163, v131
	v_fmac_f32_dpp v164, v178, v135 row_ror:15 row_mask:0xf bank_mask:0xf
	v_add_f32_e32 v164, v139, v164
	v_mul_f32_e32 v179, 0xbfb8aa3b, v164
	v_exp_f32_e32 v179, v179
	v_cndmask_b32_e64 v178, v159, 0, vcc
	v_cvt_pk_bf16_f32 v118, v117, v118
	v_add_f32_e32 v179, 1.0, v179
	v_rcp_f32_e32 v179, v179
	v_mul_f32_dpp v178, v178, v143 row_ror:1 row_mask:0xf bank_mask:0xf bound_ctrl:1
	v_fmac_f32_e32 v178, v159, v147
	v_fmac_f32_dpp v178, v180, v151 row_ror:15 row_mask:0xf bank_mask:0xf
	v_add_f32_e32 v178, v155, v178
	v_mul_f32_e32 v164, v164, v179
	v_mul_f32_e32 v164, v178, v164
	v_lshlrev_b32_e32 v178, 1, v116
	v_cvt_pk_bf16_f32 v119, v119, v164
	s_and_saveexec_b64 s[10:11], s[36:37]
	s_cbranch_execz .LBB0_1407
	v_mov_b64_e32 v[116:117], s[0:1]
	v_mad_i64_i32 v[116:117], s[38:39], v183, s66, v[116:117]
	v_lshl_add_u64 v[116:117], s[16:17], 1, v[116:117]
	s_lshl_b32 s48, s5, 1
	v_lshl_add_u64 v[116:117], v[116:117], 0, s[48:49]
	v_mov_b32_e32 v179, v165
	v_lshl_add_u64 v[116:117], v[116:117], 0, v[178:179]
	v_cvt_pk_bf16_f32 v180, v160, v161
	v_cvt_pk_bf16_f32 v181, v162, v163
	global_store_dwordx2 v[116:117], v[180:181], off
	v_cvt_pk_bf16_f32 v180, v156, v157
	v_cvt_pk_bf16_f32 v181, v158, v159
	global_store_dwordx2 v[116:117], v[180:181], off offset:256
.LBB0_1407:
	s_or_b64 exec, exec, s[10:11]
	v_cndmask_b32_e32 v116, v120, v160, vcc
	v_cndmask_b32_e64 v117, v120, v108, s[34:35]
	s_nop 0
	v_mul_f32_dpp v116, v116, v124 row_ror:1 row_mask:0xf bank_mask:0xf bound_ctrl:1
	v_fmac_f32_e32 v116, v120, v128
	v_fmac_f32_dpp v116, v117, v132 row_ror:15 row_mask:0xf bank_mask:0xf
	v_add_f32_e32 v116, v136, v116
	v_mul_f32_e32 v160, 0xbfb8aa3b, v116
	v_exp_f32_e32 v160, v160
	v_cndmask_b32_e32 v117, v112, v156, vcc
	v_cndmask_b32_e64 v156, v112, v104, s[34:35]
	s_nop 0
	v_mul_f32_dpp v117, v117, v140 row_ror:1 row_mask:0xf bank_mask:0xf bound_ctrl:1
	v_fmac_f32_e32 v117, v112, v144
	v_mov_b32_dpp v164, v156 row_ror:15 row_mask:0xf bank_mask:0xf
	v_add_f32_e32 v156, 1.0, v160
	v_rcp_f32_e32 v156, v156
	v_fmac_f32_e32 v117, v148, v164
	v_add_f32_e32 v117, v152, v117
	v_mul_f32_e32 v116, v116, v156
	v_mul_f32_e32 v116, v117, v116
	v_cndmask_b32_e32 v117, v121, v161, vcc
	v_cndmask_b32_e64 v156, v121, v109, s[34:35]
	s_nop 0
	v_mul_f32_dpp v117, v117, v125 row_ror:1 row_mask:0xf bank_mask:0xf bound_ctrl:1
	v_fmac_f32_e32 v117, v121, v129
	v_fmac_f32_dpp v117, v156, v133 row_ror:15 row_mask:0xf bank_mask:0xf
	v_add_f32_e32 v117, v137, v117
	v_mul_f32_e32 v160, 0xbfb8aa3b, v117
	v_exp_f32_e32 v160, v160
	v_cndmask_b32_e32 v156, v113, v157, vcc
	v_cndmask_b32_e64 v157, v113, v105, s[34:35]
	v_cndmask_b32_e32 v120, v108, v120, vcc
	v_mul_f32_dpp v156, v156, v141 row_ror:1 row_mask:0xf bank_mask:0xf bound_ctrl:1
	v_mov_b32_dpp v161, v157 row_ror:15 row_mask:0xf bank_mask:0xf
	v_add_f32_e32 v157, 1.0, v160
	v_rcp_f32_e32 v157, v157
	v_fmac_f32_e32 v156, v113, v145
	v_fmac_f32_e32 v156, v149, v161
	v_add_f32_e32 v156, v153, v156
	v_mul_f32_e32 v117, v117, v157
	v_mul_f32_e32 v117, v156, v117
	v_cndmask_b32_e32 v156, v122, v162, vcc
	v_cndmask_b32_e64 v157, v122, v110, s[34:35]
	s_nop 0
	v_mul_f32_dpp v156, v156, v126 row_ror:1 row_mask:0xf bank_mask:0xf bound_ctrl:1
	v_fmac_f32_e32 v156, v122, v130
	v_fmac_f32_dpp v156, v157, v134 row_ror:15 row_mask:0xf bank_mask:0xf
	v_add_f32_e32 v156, v138, v156
	v_mul_f32_e32 v160, 0xbfb8aa3b, v156
	v_exp_f32_e32 v160, v160
	v_cndmask_b32_e32 v157, v114, v158, vcc
	v_cndmask_b32_e64 v158, v114, v106, s[34:35]
	s_nop 0
	v_mul_f32_dpp v157, v157, v142 row_ror:1 row_mask:0xf bank_mask:0xf bound_ctrl:1
	v_fmac_f32_e32 v157, v114, v146
	v_mov_b32_dpp v161, v158 row_ror:15 row_mask:0xf bank_mask:0xf
	v_add_f32_e32 v158, 1.0, v160
	v_rcp_f32_e32 v158, v158
	v_fmac_f32_e32 v157, v150, v161
	v_add_f32_e32 v157, v154, v157
	v_mul_f32_e32 v156, v156, v158
	v_mul_f32_e32 v156, v157, v156
	v_cndmask_b32_e32 v157, v123, v163, vcc
	v_cndmask_b32_e64 v158, v123, v111, s[34:35]
	s_nop 0
	v_mul_f32_dpp v157, v157, v127 row_ror:1 row_mask:0xf bank_mask:0xf bound_ctrl:1
	v_fmac_f32_e32 v157, v123, v131
	v_fmac_f32_dpp v157, v158, v135 row_ror:15 row_mask:0xf bank_mask:0xf
	v_add_f32_e32 v157, v139, v157
	v_mul_f32_e32 v160, 0xbfb8aa3b, v157
	v_exp_f32_e32 v160, v160
	v_cndmask_b32_e32 v158, v115, v159, vcc
	v_cndmask_b32_e64 v159, v115, v107, s[34:35]
	v_cvt_pk_bf16_f32 v116, v116, v117
	v_mul_f32_dpp v120, v120, v124 row_ror:1 row_mask:0xf bank_mask:0xf bound_ctrl:1
	v_mul_f32_dpp v158, v158, v143 row_ror:1 row_mask:0xf bank_mask:0xf bound_ctrl:1
	v_mov_b32_dpp v161, v159 row_ror:15 row_mask:0xf bank_mask:0xf
	v_add_f32_e32 v159, 1.0, v160
	v_rcp_f32_e32 v159, v159
	v_fmac_f32_e32 v158, v115, v147
	v_fmac_f32_e32 v158, v151, v161
	v_add_f32_e32 v158, v155, v158
	v_mul_f32_e32 v157, v157, v159
	v_mul_f32_e32 v157, v158, v157
	v_cvt_pk_bf16_f32 v117, v156, v157
	v_cndmask_b32_e64 v156, v108, v100, s[34:35]
	v_fmac_f32_e32 v120, v108, v128
	s_nop 0
	v_fmac_f32_dpp v120, v156, v132 row_ror:15 row_mask:0xf bank_mask:0xf
	v_add_f32_e32 v120, v136, v120
	v_mul_f32_e32 v157, 0xbfb8aa3b, v120
	v_exp_f32_e32 v157, v157
	v_cndmask_b32_e64 v156, v104, v96, s[34:35]
	v_cndmask_b32_e32 v112, v104, v112, vcc
	v_cndmask_b32_e32 v113, v105, v113, vcc
	v_mov_b32_dpp v158, v156 row_ror:15 row_mask:0xf bank_mask:0xf
	v_add_f32_e32 v156, 1.0, v157
	v_rcp_f32_e32 v156, v156
	v_mul_f32_dpp v112, v112, v140 row_ror:1 row_mask:0xf bank_mask:0xf bound_ctrl:1
	v_fmac_f32_e32 v112, v104, v144
	v_fmac_f32_e32 v112, v148, v158
	v_add_f32_e32 v112, v152, v112
	v_mul_f32_e32 v120, v120, v156
	v_mul_f32_e32 v112, v112, v120
	v_cndmask_b32_e32 v120, v109, v121, vcc
	v_cndmask_b32_e64 v121, v109, v101, s[34:35]
	s_nop 0
	v_mul_f32_dpp v120, v120, v125 row_ror:1 row_mask:0xf bank_mask:0xf bound_ctrl:1
	v_fmac_f32_e32 v120, v109, v129
	v_fmac_f32_dpp v120, v121, v133 row_ror:15 row_mask:0xf bank_mask:0xf
	v_add_f32_e32 v120, v137, v120
	v_mul_f32_e32 v156, 0xbfb8aa3b, v120
	v_exp_f32_e32 v156, v156
	v_cndmask_b32_e64 v121, v105, v97, s[34:35]
	v_mul_f32_dpp v113, v113, v141 row_ror:1 row_mask:0xf bank_mask:0xf bound_ctrl:1
	v_fmac_f32_e32 v113, v105, v145
	v_mov_b32_dpp v157, v121 row_ror:15 row_mask:0xf bank_mask:0xf
	v_add_f32_e32 v121, 1.0, v156
	v_rcp_f32_e32 v121, v121
	v_fmac_f32_e32 v113, v149, v157
	v_add_f32_e32 v113, v153, v113
	v_mul_f32_e32 v120, v120, v121
	v_mul_f32_e32 v113, v113, v120
	v_cndmask_b32_e32 v120, v110, v122, vcc
	v_cndmask_b32_e64 v121, v110, v102, s[34:35]
	s_nop 0
	v_mul_f32_dpp v120, v120, v126 row_ror:1 row_mask:0xf bank_mask:0xf bound_ctrl:1
	v_fmac_f32_e32 v120, v110, v130
	v_fmac_f32_dpp v120, v121, v134 row_ror:15 row_mask:0xf bank_mask:0xf
	v_add_f32_e32 v120, v138, v120
	v_mul_f32_e32 v122, 0xbfb8aa3b, v120
	v_exp_f32_e32 v122, v122
	v_cndmask_b32_e64 v121, v106, v98, s[34:35]
	v_cndmask_b32_e32 v114, v106, v114, vcc
	v_cndmask_b32_e32 v115, v107, v115, vcc
	v_mov_b32_dpp v156, v121 row_ror:15 row_mask:0xf bank_mask:0xf
	v_add_f32_e32 v121, 1.0, v122
	v_rcp_f32_e32 v121, v121
	v_mul_f32_dpp v114, v114, v142 row_ror:1 row_mask:0xf bank_mask:0xf bound_ctrl:1
	v_fmac_f32_e32 v114, v106, v146
	v_fmac_f32_e32 v114, v150, v156
	v_add_f32_e32 v114, v154, v114
	v_mul_f32_e32 v120, v120, v121
	v_mul_f32_e32 v114, v114, v120
	v_cndmask_b32_e32 v120, v111, v123, vcc
	v_cndmask_b32_e64 v121, v111, v103, s[34:35]
	s_nop 0
	v_mul_f32_dpp v120, v120, v127 row_ror:1 row_mask:0xf bank_mask:0xf bound_ctrl:1
	v_fmac_f32_e32 v120, v111, v131
	v_fmac_f32_dpp v120, v121, v135 row_ror:15 row_mask:0xf bank_mask:0xf
	v_add_f32_e32 v120, v139, v120
	v_mul_f32_e32 v122, 0xbfb8aa3b, v120
	v_exp_f32_e32 v122, v122
	v_cndmask_b32_e64 v121, v107, v99, s[34:35]
	v_mul_f32_dpp v115, v115, v143 row_ror:1 row_mask:0xf bank_mask:0xf bound_ctrl:1
	v_fmac_f32_e32 v115, v107, v147
	v_mov_b32_dpp v123, v121 row_ror:15 row_mask:0xf bank_mask:0xf
	v_add_f32_e32 v121, 1.0, v122
	v_rcp_f32_e32 v121, v121
	v_fmac_f32_e32 v115, v151, v123
	v_add_f32_e32 v115, v155, v115
	v_cndmask_b32_e32 v108, v100, v108, vcc
	v_mul_f32_e32 v120, v120, v121
	v_mul_f32_e32 v115, v115, v120
	v_cvt_pk_bf16_f32 v112, v112, v113
	v_cvt_pk_bf16_f32 v113, v114, v115
	v_cndmask_b32_e64 v114, v100, 0, s[34:35]
	v_mul_f32_dpp v108, v108, v124 row_ror:1 row_mask:0xf bank_mask:0xf bound_ctrl:1
	v_fmac_f32_e32 v108, v100, v128
	v_fmac_f32_dpp v108, v114, v132 row_ror:15 row_mask:0xf bank_mask:0xf
	v_add_f32_e32 v108, v136, v108
	v_mul_f32_e32 v115, 0xbfb8aa3b, v108
	v_exp_f32_e32 v115, v115
	v_cndmask_b32_e64 v114, v96, 0, s[34:35]
	v_cndmask_b32_e32 v104, v96, v104, vcc
	v_cndmask_b32_e32 v105, v97, v105, vcc
	v_mov_b32_dpp v120, v114 row_ror:15 row_mask:0xf bank_mask:0xf
	v_add_f32_e32 v114, 1.0, v115
	v_rcp_f32_e32 v114, v114
	v_mul_f32_dpp v104, v104, v140 row_ror:1 row_mask:0xf bank_mask:0xf bound_ctrl:1
	v_fmac_f32_e32 v104, v96, v144
	v_fmac_f32_e32 v104, v148, v120
	v_add_f32_e32 v104, v152, v104
	v_mul_f32_e32 v108, v108, v114
	v_mul_f32_e32 v104, v104, v108
	v_cndmask_b32_e32 v108, v101, v109, vcc
	v_cndmask_b32_e64 v109, v101, 0, s[34:35]
	s_nop 0
	v_mul_f32_dpp v108, v108, v125 row_ror:1 row_mask:0xf bank_mask:0xf bound_ctrl:1
	v_fmac_f32_e32 v108, v101, v129
	v_fmac_f32_dpp v108, v109, v133 row_ror:15 row_mask:0xf bank_mask:0xf
	v_add_f32_e32 v108, v137, v108
	v_mul_f32_e32 v114, 0xbfb8aa3b, v108
	v_exp_f32_e32 v114, v114
	v_cndmask_b32_e64 v109, v97, 0, s[34:35]
	v_mul_f32_dpp v105, v105, v141 row_ror:1 row_mask:0xf bank_mask:0xf bound_ctrl:1
	v_fmac_f32_e32 v105, v97, v145
	v_mov_b32_dpp v115, v109 row_ror:15 row_mask:0xf bank_mask:0xf
	v_add_f32_e32 v109, 1.0, v114
	v_rcp_f32_e32 v109, v109
	v_fmac_f32_e32 v105, v149, v115
	v_add_f32_e32 v105, v153, v105
	v_mul_f32_e32 v108, v108, v109
	v_mul_f32_e32 v105, v105, v108
	v_cndmask_b32_e32 v108, v102, v110, vcc
	v_cndmask_b32_e64 v109, v102, 0, s[34:35]
	s_nop 0
	v_mul_f32_dpp v108, v108, v126 row_ror:1 row_mask:0xf bank_mask:0xf bound_ctrl:1
	v_fmac_f32_e32 v108, v102, v130
	v_fmac_f32_dpp v108, v109, v134 row_ror:15 row_mask:0xf bank_mask:0xf
	v_add_f32_e32 v108, v138, v108
	v_mul_f32_e32 v110, 0xbfb8aa3b, v108
	v_exp_f32_e32 v110, v110
	v_cndmask_b32_e64 v109, v98, 0, s[34:35]
	v_cndmask_b32_e32 v106, v98, v106, vcc
	v_cndmask_b32_e32 v107, v99, v107, vcc
	v_mov_b32_dpp v114, v109 row_ror:15 row_mask:0xf bank_mask:0xf
	v_add_f32_e32 v109, 1.0, v110
	v_rcp_f32_e32 v109, v109
	v_mul_f32_dpp v106, v106, v142 row_ror:1 row_mask:0xf bank_mask:0xf bound_ctrl:1
	v_fmac_f32_e32 v106, v98, v146
	v_fmac_f32_e32 v106, v150, v114
	v_add_f32_e32 v106, v154, v106
	v_mul_f32_e32 v108, v108, v109
	v_mul_f32_e32 v106, v106, v108
	v_cndmask_b32_e32 v108, v103, v111, vcc
	v_cndmask_b32_e64 v109, v103, 0, s[34:35]
	s_nop 0
	v_mul_f32_dpp v108, v108, v127 row_ror:1 row_mask:0xf bank_mask:0xf bound_ctrl:1
	v_fmac_f32_e32 v108, v103, v131
	v_fmac_f32_dpp v108, v109, v135 row_ror:15 row_mask:0xf bank_mask:0xf
	v_add_f32_e32 v108, v139, v108
	v_mul_f32_e32 v110, 0xbfb8aa3b, v108
	v_exp_f32_e32 v110, v110
	v_cndmask_b32_e64 v109, v99, 0, s[34:35]
	v_mul_f32_dpp v107, v107, v143 row_ror:1 row_mask:0xf bank_mask:0xf bound_ctrl:1
	v_fmac_f32_e32 v107, v99, v147
	v_mov_b32_dpp v111, v109 row_ror:15 row_mask:0xf bank_mask:0xf
	v_add_f32_e32 v109, 1.0, v110
	v_rcp_f32_e32 v109, v109
	v_fmac_f32_e32 v107, v151, v111
	v_cmp_lt_u32_e64 s[38:39], 13, v200
	v_add_u32_e32 v180, -12, v200
	v_add_f32_e32 v107, v155, v107
	v_mul_f32_e32 v108, v108, v109
	v_mul_f32_e32 v107, v107, v108
	v_cvt_pk_bf16_f32 v104, v104, v105
	v_cvt_pk_bf16_f32 v105, v106, v107
	s_and_saveexec_b64 s[10:11], s[38:39]
	s_cbranch_execz .LBB0_1409
	v_mov_b32_e32 v181, v165
	v_lshl_add_u64 v[106:107], s[52:53], 0, v[180:181]
	v_mov_b64_e32 v[108:109], s[0:1]
	s_movk_i32 s48, 0x2c00
	v_mad_u64_u32 v[108:109], s[40:41], v106, s48, v[108:109]
	v_mad_i32_i24 v109, v107, s48, v109
	v_lshl_add_u64 v[106:107], s[16:17], 1, v[108:109]
	s_lshl_b32 s48, s5, 1
	v_lshl_add_u64 v[106:107], v[106:107], 0, s[48:49]
	v_mov_b32_e32 v179, v165
	s_movk_i32 s66, 0x2c00
	v_lshl_add_u64 v[106:107], v[106:107], 0, v[178:179]
	v_cvt_pk_bf16_f32 v100, v100, v101
	v_cvt_pk_bf16_f32 v101, v102, v103
	global_store_dwordx2 v[106:107], v[100:101], off
	v_cvt_pk_bf16_f32 v96, v96, v97
	v_cvt_pk_bf16_f32 v97, v98, v99
	global_store_dwordx2 v[106:107], v[96:97], off offset:256
.LBB0_1409:
	s_or_b64 exec, exec, s[10:11]
	v_cndmask_b32_e64 v96, v92, 0, vcc
	v_cndmask_b32_e64 v97, v92, v84, s[34:35]
	s_nop 0
	v_mul_f32_dpp v96, v96, v124 row_ror:1 row_mask:0xf bank_mask:0xf bound_ctrl:1
	v_fmac_f32_e32 v96, v92, v128
	v_fmac_f32_dpp v96, v97, v132 row_ror:15 row_mask:0xf bank_mask:0xf
	v_add_f32_e32 v96, v136, v96
	v_mul_f32_e32 v98, 0xbfb8aa3b, v96
	v_exp_f32_e32 v98, v98
	v_cndmask_b32_e64 v97, v88, 0, vcc
	v_cndmask_b32_e64 v99, v88, v80, s[34:35]
	v_add_f32_e32 v98, 1.0, v98
	v_rcp_f32_e32 v98, v98
	v_mul_f32_dpp v97, v97, v140 row_ror:1 row_mask:0xf bank_mask:0xf bound_ctrl:1
	v_fmac_f32_e32 v97, v88, v144
	v_fmac_f32_dpp v97, v99, v148 row_ror:15 row_mask:0xf bank_mask:0xf
	v_add_f32_e32 v97, v152, v97
	v_mul_f32_e32 v96, v96, v98
	v_mul_f32_e32 v96, v97, v96
	v_cndmask_b32_e64 v97, v93, 0, vcc
	v_cndmask_b32_e64 v98, v93, v85, s[34:35]
	s_nop 0
	v_mul_f32_dpp v97, v97, v125 row_ror:1 row_mask:0xf bank_mask:0xf bound_ctrl:1
	v_fmac_f32_e32 v97, v93, v129
	v_fmac_f32_dpp v97, v98, v133 row_ror:15 row_mask:0xf bank_mask:0xf
	v_add_f32_e32 v97, v137, v97
	v_mul_f32_e32 v99, 0xbfb8aa3b, v97
	v_exp_f32_e32 v99, v99
	v_cndmask_b32_e64 v98, v89, 0, vcc
	v_cndmask_b32_e64 v100, v89, v81, s[34:35]
	v_add_f32_e32 v99, 1.0, v99
	v_rcp_f32_e32 v99, v99
	v_mul_f32_dpp v98, v98, v141 row_ror:1 row_mask:0xf bank_mask:0xf bound_ctrl:1
	v_fmac_f32_e32 v98, v89, v145
	v_fmac_f32_dpp v98, v100, v149 row_ror:15 row_mask:0xf bank_mask:0xf
	v_add_f32_e32 v98, v153, v98
	v_mul_f32_e32 v97, v97, v99
	v_mul_f32_e32 v97, v98, v97
	v_cndmask_b32_e64 v98, v94, 0, vcc
	v_cndmask_b32_e64 v99, v94, v86, s[34:35]
	s_nop 0
	v_mul_f32_dpp v98, v98, v126 row_ror:1 row_mask:0xf bank_mask:0xf bound_ctrl:1
	v_fmac_f32_e32 v98, v94, v130
	v_fmac_f32_dpp v98, v99, v134 row_ror:15 row_mask:0xf bank_mask:0xf
	v_add_f32_e32 v98, v138, v98
	v_mul_f32_e32 v100, 0xbfb8aa3b, v98
	v_exp_f32_e32 v100, v100
	v_cndmask_b32_e64 v99, v90, 0, vcc
	v_cndmask_b32_e64 v101, v90, v82, s[34:35]
	v_add_f32_e32 v100, 1.0, v100
	v_rcp_f32_e32 v100, v100
	v_mul_f32_dpp v99, v99, v142 row_ror:1 row_mask:0xf bank_mask:0xf bound_ctrl:1
	v_fmac_f32_e32 v99, v90, v146
	v_fmac_f32_dpp v99, v101, v150 row_ror:15 row_mask:0xf bank_mask:0xf
	v_add_f32_e32 v99, v154, v99
	v_mul_f32_e32 v98, v98, v100
	v_mul_f32_e32 v98, v99, v98
	v_cndmask_b32_e64 v99, v95, 0, vcc
	v_cndmask_b32_e64 v100, v95, v87, s[34:35]
	s_nop 0
	v_mul_f32_dpp v99, v99, v127 row_ror:1 row_mask:0xf bank_mask:0xf bound_ctrl:1
	v_fmac_f32_e32 v99, v95, v131
	v_fmac_f32_dpp v99, v100, v135 row_ror:15 row_mask:0xf bank_mask:0xf
	v_add_f32_e32 v99, v139, v99
	v_mul_f32_e32 v101, 0xbfb8aa3b, v99
	v_exp_f32_e32 v101, v101
	s_add_i32 s85, s31, 0x80
	v_cndmask_b32_e64 v100, v91, 0, vcc
	s_ashr_i32 s10, s85, 6
	v_add_f32_e32 v101, 1.0, v101
	v_rcp_f32_e32 v101, v101
	v_cndmask_b32_e64 v102, v91, v83, s[34:35]
	v_mul_f32_dpp v100, v100, v143 row_ror:1 row_mask:0xf bank_mask:0xf bound_ctrl:1
	s_ashr_i32 s11, s10, 31
	v_fmac_f32_e32 v100, v91, v147
	s_lshl_b64 s[10:11], s[10:11], 2
	v_fmac_f32_dpp v100, v102, v151 row_ror:15 row_mask:0xf bank_mask:0xf
	v_add_f32_e32 v100, v155, v100
	v_mul_f32_e32 v99, v99, v101
	v_or_b32_e32 v156, s10, v200
	v_mul_f32_e32 v99, v100, v99
	v_cvt_pk_bf16_f32 v96, v96, v97
	v_cvt_pk_bf16_f32 v97, v98, v99
	s_and_saveexec_b64 s[40:41], s[36:37]
	s_cbranch_execz .LBB0_1411
	v_mov_b64_e32 v[98:99], s[0:1]
	v_mad_i64_i32 v[98:99], s[86:87], v156, s66, v[98:99]
	v_lshl_add_u64 v[98:99], s[16:17], 1, v[98:99]
	s_lshl_b32 s48, s5, 1
	v_lshl_add_u64 v[98:99], v[98:99], 0, s[48:49]
	v_mov_b32_e32 v179, v165
	v_lshl_add_u64 v[98:99], v[98:99], 0, v[178:179]
	v_cvt_pk_bf16_f32 v100, v92, v93
	v_cvt_pk_bf16_f32 v101, v94, v95
	global_store_dwordx2 v[98:99], v[100:101], off
	v_cvt_pk_bf16_f32 v100, v88, v89
	v_cvt_pk_bf16_f32 v101, v90, v91
	global_store_dwordx2 v[98:99], v[100:101], off offset:256
.LBB0_1411:
	s_or_b64 exec, exec, s[40:41]
	v_cndmask_b32_e32 v92, v84, v92, vcc
	v_cndmask_b32_e64 v98, v84, v76, s[34:35]
	s_nop 0
	v_mul_f32_dpp v92, v92, v124 row_ror:1 row_mask:0xf bank_mask:0xf bound_ctrl:1
	v_fmac_f32_e32 v92, v84, v128
	v_fmac_f32_dpp v92, v98, v132 row_ror:15 row_mask:0xf bank_mask:0xf
	v_add_f32_e32 v92, v136, v92
	v_mul_f32_e32 v99, 0xbfb8aa3b, v92
	v_exp_f32_e32 v99, v99
	v_cndmask_b32_e64 v98, v80, v72, s[34:35]
	v_cndmask_b32_e32 v88, v80, v88, vcc
	v_cndmask_b32_e32 v89, v81, v89, vcc
	v_mov_b32_dpp v100, v98 row_ror:15 row_mask:0xf bank_mask:0xf
	v_add_f32_e32 v98, 1.0, v99
	v_rcp_f32_e32 v98, v98
	v_mul_f32_dpp v88, v88, v140 row_ror:1 row_mask:0xf bank_mask:0xf bound_ctrl:1
	v_fmac_f32_e32 v88, v80, v144
	v_fmac_f32_e32 v88, v148, v100
	v_add_f32_e32 v88, v152, v88
	v_mul_f32_e32 v92, v92, v98
	v_mul_f32_e32 v88, v88, v92
	v_cndmask_b32_e32 v92, v85, v93, vcc
	v_cndmask_b32_e64 v93, v85, v77, s[34:35]
	s_nop 0
	v_mul_f32_dpp v92, v92, v125 row_ror:1 row_mask:0xf bank_mask:0xf bound_ctrl:1
	v_fmac_f32_e32 v92, v85, v129
	v_fmac_f32_dpp v92, v93, v133 row_ror:15 row_mask:0xf bank_mask:0xf
	v_add_f32_e32 v92, v137, v92
	v_mul_f32_e32 v98, 0xbfb8aa3b, v92
	v_exp_f32_e32 v98, v98
	v_cndmask_b32_e64 v93, v81, v73, s[34:35]
	v_mul_f32_dpp v89, v89, v141 row_ror:1 row_mask:0xf bank_mask:0xf bound_ctrl:1
	v_fmac_f32_e32 v89, v81, v145
	v_mov_b32_dpp v99, v93 row_ror:15 row_mask:0xf bank_mask:0xf
	v_add_f32_e32 v93, 1.0, v98
	v_rcp_f32_e32 v93, v93
	v_fmac_f32_e32 v89, v149, v99
	v_add_f32_e32 v89, v153, v89
	v_mul_f32_e32 v92, v92, v93
	v_mul_f32_e32 v89, v89, v92
	v_cndmask_b32_e32 v92, v86, v94, vcc
	v_cndmask_b32_e64 v93, v86, v78, s[34:35]
	s_nop 0
	v_mul_f32_dpp v92, v92, v126 row_ror:1 row_mask:0xf bank_mask:0xf bound_ctrl:1
	v_fmac_f32_e32 v92, v86, v130
	v_fmac_f32_dpp v92, v93, v134 row_ror:15 row_mask:0xf bank_mask:0xf
	v_add_f32_e32 v92, v138, v92
	v_mul_f32_e32 v94, 0xbfb8aa3b, v92
	v_exp_f32_e32 v94, v94
	v_cndmask_b32_e64 v93, v82, v74, s[34:35]
	v_cndmask_b32_e32 v90, v82, v90, vcc
	v_cndmask_b32_e32 v91, v83, v91, vcc
	v_mov_b32_dpp v98, v93 row_ror:15 row_mask:0xf bank_mask:0xf
	v_add_f32_e32 v93, 1.0, v94
	v_rcp_f32_e32 v93, v93
	v_mul_f32_dpp v90, v90, v142 row_ror:1 row_mask:0xf bank_mask:0xf bound_ctrl:1
	v_fmac_f32_e32 v90, v82, v146
	v_fmac_f32_e32 v90, v150, v98
	v_add_f32_e32 v90, v154, v90
	v_mul_f32_e32 v92, v92, v93
	v_mul_f32_e32 v90, v90, v92
	v_cndmask_b32_e32 v92, v87, v95, vcc
	v_cndmask_b32_e64 v93, v87, v79, s[34:35]
	s_nop 0
	v_mul_f32_dpp v92, v92, v127 row_ror:1 row_mask:0xf bank_mask:0xf bound_ctrl:1
	v_fmac_f32_e32 v92, v87, v131
	v_fmac_f32_dpp v92, v93, v135 row_ror:15 row_mask:0xf bank_mask:0xf
	v_add_f32_e32 v92, v139, v92
	v_mul_f32_e32 v94, 0xbfb8aa3b, v92
	v_exp_f32_e32 v94, v94
	v_cndmask_b32_e64 v93, v83, v75, s[34:35]
	v_mul_f32_dpp v91, v91, v143 row_ror:1 row_mask:0xf bank_mask:0xf bound_ctrl:1
	v_fmac_f32_e32 v91, v83, v147
	v_mov_b32_dpp v95, v93 row_ror:15 row_mask:0xf bank_mask:0xf
	v_add_f32_e32 v93, 1.0, v94
	v_rcp_f32_e32 v93, v93
	v_fmac_f32_e32 v91, v151, v95
	v_add_f32_e32 v91, v155, v91
	v_cndmask_b32_e32 v84, v76, v84, vcc
	v_mul_f32_e32 v92, v92, v93
	v_mul_f32_e32 v91, v91, v92
	v_cvt_pk_bf16_f32 v88, v88, v89
	v_cvt_pk_bf16_f32 v89, v90, v91
	v_cndmask_b32_e64 v90, v76, v68, s[34:35]
	v_mul_f32_dpp v84, v84, v124 row_ror:1 row_mask:0xf bank_mask:0xf bound_ctrl:1
	v_fmac_f32_e32 v84, v76, v128
	v_fmac_f32_dpp v84, v90, v132 row_ror:15 row_mask:0xf bank_mask:0xf
	v_add_f32_e32 v84, v136, v84
	v_mul_f32_e32 v91, 0xbfb8aa3b, v84
	v_exp_f32_e32 v91, v91
	v_cndmask_b32_e64 v90, v72, v64, s[34:35]
	v_cndmask_b32_e32 v80, v72, v80, vcc
	v_cndmask_b32_e32 v81, v73, v81, vcc
	v_mov_b32_dpp v92, v90 row_ror:15 row_mask:0xf bank_mask:0xf
	v_add_f32_e32 v90, 1.0, v91
	v_rcp_f32_e32 v90, v90
	v_mul_f32_dpp v80, v80, v140 row_ror:1 row_mask:0xf bank_mask:0xf bound_ctrl:1
	v_fmac_f32_e32 v80, v72, v144
	v_fmac_f32_e32 v80, v148, v92
	v_add_f32_e32 v80, v152, v80
	v_mul_f32_e32 v84, v84, v90
	v_mul_f32_e32 v80, v80, v84
	v_cndmask_b32_e32 v84, v77, v85, vcc
	v_cndmask_b32_e64 v85, v77, v69, s[34:35]
	s_nop 0
	v_mul_f32_dpp v84, v84, v125 row_ror:1 row_mask:0xf bank_mask:0xf bound_ctrl:1
	v_fmac_f32_e32 v84, v77, v129
	v_fmac_f32_dpp v84, v85, v133 row_ror:15 row_mask:0xf bank_mask:0xf
	v_add_f32_e32 v84, v137, v84
	v_mul_f32_e32 v90, 0xbfb8aa3b, v84
	v_exp_f32_e32 v90, v90
	v_cndmask_b32_e64 v85, v73, v65, s[34:35]
	v_mul_f32_dpp v81, v81, v141 row_ror:1 row_mask:0xf bank_mask:0xf bound_ctrl:1
	v_fmac_f32_e32 v81, v73, v145
	v_mov_b32_dpp v91, v85 row_ror:15 row_mask:0xf bank_mask:0xf
	v_add_f32_e32 v85, 1.0, v90
	v_rcp_f32_e32 v85, v85
	v_fmac_f32_e32 v81, v149, v91
	v_add_f32_e32 v81, v153, v81
	v_mul_f32_e32 v84, v84, v85
	v_mul_f32_e32 v81, v81, v84
	v_cndmask_b32_e32 v84, v78, v86, vcc
	v_cndmask_b32_e64 v85, v78, v70, s[34:35]
	s_nop 0
	v_mul_f32_dpp v84, v84, v126 row_ror:1 row_mask:0xf bank_mask:0xf bound_ctrl:1
	v_fmac_f32_e32 v84, v78, v130
	v_fmac_f32_dpp v84, v85, v134 row_ror:15 row_mask:0xf bank_mask:0xf
	v_add_f32_e32 v84, v138, v84
	v_mul_f32_e32 v86, 0xbfb8aa3b, v84
	v_exp_f32_e32 v86, v86
	v_cndmask_b32_e64 v85, v74, v66, s[34:35]
	v_cndmask_b32_e32 v82, v74, v82, vcc
	v_cndmask_b32_e32 v83, v75, v83, vcc
	v_mov_b32_dpp v90, v85 row_ror:15 row_mask:0xf bank_mask:0xf
	v_add_f32_e32 v85, 1.0, v86
	v_rcp_f32_e32 v85, v85
	v_mul_f32_dpp v82, v82, v142 row_ror:1 row_mask:0xf bank_mask:0xf bound_ctrl:1
	v_fmac_f32_e32 v82, v74, v146
	v_fmac_f32_e32 v82, v150, v90
	v_add_f32_e32 v82, v154, v82
	v_mul_f32_e32 v84, v84, v85
	v_mul_f32_e32 v82, v82, v84
	v_cndmask_b32_e32 v84, v79, v87, vcc
	v_cndmask_b32_e64 v85, v79, v71, s[34:35]
	s_nop 0
	v_mul_f32_dpp v84, v84, v127 row_ror:1 row_mask:0xf bank_mask:0xf bound_ctrl:1
	v_fmac_f32_e32 v84, v79, v131
	v_fmac_f32_dpp v84, v85, v135 row_ror:15 row_mask:0xf bank_mask:0xf
	v_add_f32_e32 v84, v139, v84
	v_mul_f32_e32 v86, 0xbfb8aa3b, v84
	v_exp_f32_e32 v86, v86
	v_cndmask_b32_e64 v85, v75, v67, s[34:35]
	v_mul_f32_dpp v83, v83, v143 row_ror:1 row_mask:0xf bank_mask:0xf bound_ctrl:1
	v_fmac_f32_e32 v83, v75, v147
	v_mov_b32_dpp v87, v85 row_ror:15 row_mask:0xf bank_mask:0xf
	v_add_f32_e32 v85, 1.0, v86
	v_rcp_f32_e32 v85, v85
	v_fmac_f32_e32 v83, v151, v87
	v_add_f32_e32 v83, v155, v83
	v_cndmask_b32_e32 v76, v68, v76, vcc
	v_mul_f32_e32 v84, v84, v85
	v_mul_f32_e32 v83, v83, v84
	v_cvt_pk_bf16_f32 v80, v80, v81
	v_cvt_pk_bf16_f32 v81, v82, v83
	v_cndmask_b32_e64 v82, v68, 0, s[34:35]
	v_mul_f32_dpp v76, v76, v124 row_ror:1 row_mask:0xf bank_mask:0xf bound_ctrl:1
	v_fmac_f32_e32 v76, v68, v128
	v_fmac_f32_dpp v76, v82, v132 row_ror:15 row_mask:0xf bank_mask:0xf
	v_add_f32_e32 v76, v136, v76
	v_mul_f32_e32 v83, 0xbfb8aa3b, v76
	v_exp_f32_e32 v83, v83
	v_cndmask_b32_e64 v82, v64, 0, s[34:35]
	v_cndmask_b32_e32 v72, v64, v72, vcc
	v_cndmask_b32_e32 v73, v65, v73, vcc
	v_mov_b32_dpp v84, v82 row_ror:15 row_mask:0xf bank_mask:0xf
	v_add_f32_e32 v82, 1.0, v83
	v_rcp_f32_e32 v82, v82
	v_mul_f32_dpp v72, v72, v140 row_ror:1 row_mask:0xf bank_mask:0xf bound_ctrl:1
	v_fmac_f32_e32 v72, v64, v144
	v_fmac_f32_e32 v72, v148, v84
	v_add_f32_e32 v72, v152, v72
	v_mul_f32_e32 v76, v76, v82
	v_mul_f32_e32 v72, v72, v76
	v_cndmask_b32_e32 v76, v69, v77, vcc
	v_cndmask_b32_e64 v77, v69, 0, s[34:35]
	s_nop 0
	v_mul_f32_dpp v76, v76, v125 row_ror:1 row_mask:0xf bank_mask:0xf bound_ctrl:1
	v_fmac_f32_e32 v76, v69, v129
	v_fmac_f32_dpp v76, v77, v133 row_ror:15 row_mask:0xf bank_mask:0xf
	v_add_f32_e32 v76, v137, v76
	v_mul_f32_e32 v82, 0xbfb8aa3b, v76
	v_exp_f32_e32 v82, v82
	v_cndmask_b32_e64 v77, v65, 0, s[34:35]
	v_mul_f32_dpp v73, v73, v141 row_ror:1 row_mask:0xf bank_mask:0xf bound_ctrl:1
	v_fmac_f32_e32 v73, v65, v145
	v_mov_b32_dpp v83, v77 row_ror:15 row_mask:0xf bank_mask:0xf
	v_add_f32_e32 v77, 1.0, v82
	v_rcp_f32_e32 v77, v77
	v_fmac_f32_e32 v73, v149, v83
	v_add_f32_e32 v73, v153, v73
	v_mul_f32_e32 v76, v76, v77
	v_mul_f32_e32 v73, v73, v76
	v_cndmask_b32_e32 v76, v70, v78, vcc
	v_cndmask_b32_e64 v77, v70, 0, s[34:35]
	s_nop 0
	v_mul_f32_dpp v76, v76, v126 row_ror:1 row_mask:0xf bank_mask:0xf bound_ctrl:1
	v_fmac_f32_e32 v76, v70, v130
	v_fmac_f32_dpp v76, v77, v134 row_ror:15 row_mask:0xf bank_mask:0xf
	v_add_f32_e32 v76, v138, v76
	v_mul_f32_e32 v78, 0xbfb8aa3b, v76
	v_exp_f32_e32 v78, v78
	v_cndmask_b32_e64 v77, v66, 0, s[34:35]
	v_cndmask_b32_e32 v74, v66, v74, vcc
	v_cndmask_b32_e32 v75, v67, v75, vcc
	v_mov_b32_dpp v82, v77 row_ror:15 row_mask:0xf bank_mask:0xf
	v_add_f32_e32 v77, 1.0, v78
	v_rcp_f32_e32 v77, v77
	v_mul_f32_dpp v74, v74, v142 row_ror:1 row_mask:0xf bank_mask:0xf bound_ctrl:1
	v_fmac_f32_e32 v74, v66, v146
	v_fmac_f32_e32 v74, v150, v82
	v_add_f32_e32 v74, v154, v74
	v_mul_f32_e32 v76, v76, v77
	v_mul_f32_e32 v74, v74, v76
	v_cndmask_b32_e32 v76, v71, v79, vcc
	v_cndmask_b32_e64 v77, v71, 0, s[34:35]
	s_nop 0
	v_mul_f32_dpp v76, v76, v127 row_ror:1 row_mask:0xf bank_mask:0xf bound_ctrl:1
	v_fmac_f32_e32 v76, v71, v131
	v_fmac_f32_dpp v76, v77, v135 row_ror:15 row_mask:0xf bank_mask:0xf
	v_add_f32_e32 v76, v139, v76
	v_mul_f32_e32 v78, 0xbfb8aa3b, v76
	v_exp_f32_e32 v78, v78
	v_cndmask_b32_e64 v77, v67, 0, s[34:35]
	v_mul_f32_dpp v75, v75, v143 row_ror:1 row_mask:0xf bank_mask:0xf bound_ctrl:1
	v_fmac_f32_e32 v75, v67, v147
	v_mov_b32_dpp v79, v77 row_ror:15 row_mask:0xf bank_mask:0xf
	v_add_f32_e32 v77, 1.0, v78
	v_rcp_f32_e32 v77, v77
	v_fmac_f32_e32 v75, v151, v79
	v_add_f32_e32 v75, v155, v75
	v_cvt_pk_bf16_f32 v72, v72, v73
	v_mul_f32_e32 v76, v76, v77
	v_mul_f32_e32 v75, v75, v76
	v_cvt_pk_bf16_f32 v73, v74, v75
	s_and_saveexec_b64 s[40:41], s[38:39]
	s_cbranch_execz .LBB0_1413
	v_mov_b32_e32 v181, v165
	v_lshl_add_u64 v[74:75], s[10:11], 0, v[180:181]
	v_mov_b64_e32 v[76:77], s[0:1]
	s_movk_i32 s48, 0x2c00
	v_mad_u64_u32 v[76:77], s[86:87], v74, s48, v[76:77]
	v_mad_i32_i24 v77, v75, s48, v77
	v_lshl_add_u64 v[74:75], s[16:17], 1, v[76:77]
	s_lshl_b32 s48, s5, 1
	v_lshl_add_u64 v[74:75], v[74:75], 0, s[48:49]
	v_mov_b32_e32 v179, v165
	s_movk_i32 s66, 0x2c00
	v_lshl_add_u64 v[74:75], v[74:75], 0, v[178:179]
	v_cvt_pk_bf16_f32 v68, v68, v69
	v_cvt_pk_bf16_f32 v69, v70, v71
	global_store_dwordx2 v[74:75], v[68:69], off
	v_cvt_pk_bf16_f32 v64, v64, v65
	v_cvt_pk_bf16_f32 v65, v66, v67
	global_store_dwordx2 v[74:75], v[64:65], off offset:256
.LBB0_1413:
	s_or_b64 exec, exec, s[40:41]
	v_or_b32_e32 v68, 4, v182
	v_ashrrev_i32_e32 v69, 31, v68
	v_lshlrev_b64 v[82:83], 2, v[68:69]
	global_load_dwordx4 v[64:67], v[184:185], off offset:16
	v_lshl_add_u64 v[68:69], s[58:59], 0, v[82:83]
	global_load_dwordx4 v[68:71], v[68:69], off
	v_lshl_add_u64 v[74:75], s[60:61], 0, v[82:83]
	global_load_dwordx4 v[74:77], v[74:75], off
	s_nop 0
	global_load_dwordx4 v[84:87], v[186:187], off offset:16
	v_lshl_add_u64 v[90:91], s[12:13], 0, v[82:83]
	global_load_dwordx4 v[92:95], v[90:91], off
	v_lshl_add_u64 v[90:91], s[50:51], 0, v[82:83]
	global_load_dwordx4 v[100:103], v[90:91], off
	v_lshl_add_u64 v[90:91], s[20:21], 0, v[82:83]
	global_load_dwordx4 v[108:111], v[90:91], off
	v_lshl_add_u64 v[82:83], s[44:45], 0, v[82:83]
	global_load_dwordx4 v[122:125], v[82:83], off
	v_cndmask_b32_e64 v79, v60, 0, vcc
	v_cndmask_b32_e64 v83, v60, v52, s[34:35]
	v_cndmask_b32_e64 v91, v56, v48, s[34:35]
	s_nop 0
	v_mov_b32_dpp v90, v83 row_ror:15 row_mask:0xf bank_mask:0xf
	v_cndmask_b32_e64 v83, v56, 0, vcc
	v_mov_b32_dpp v98, v91 row_ror:15 row_mask:0xf bank_mask:0xf
	v_mov_b32_e32 v106, v165
	s_ashr_i32 s40, s6, 6
	s_ashr_i32 s41, s40, 31
	s_ashr_i32 s31, s31, 8
	s_lshl_b64 s[40:41], s[40:41], 15
	v_or_b32_e32 v78, s7, v200
	v_mov_b32_e32 v107, v165
	s_add_u32 s86, s80, s40
	s_mul_hi_i32 s7, s31, 0x160000
	s_mul_i32 s31, s31, 0x160000
	v_and_b32_e32 v82, 56, v182
	v_lshlrev_b32_e32 v78, 6, v78
	s_movk_i32 s6, 0x33c0
	s_addc_u32 s87, s81, s41
	v_and_or_b32 v78, v78, s6, v82
	s_add_u32 s40, s86, s31
	s_addc_u32 s41, s87, s7
	v_lshlrev_b32_e32 v164, 1, v78
	s_waitcnt vmcnt(0)
	v_mul_f32_dpp v79, v79, v64 row_ror:1 row_mask:0xf bank_mask:0xf bound_ctrl:1
	v_fmac_f32_e32 v79, v60, v68
	v_fmac_f32_e32 v79, v74, v90
	v_add_f32_e32 v79, v84, v79
	v_mul_f32_e32 v90, 0xbfb8aa3b, v79
	v_exp_f32_e32 v90, v90
	v_mul_f32_dpp v83, v83, v92 row_ror:1 row_mask:0xf bank_mask:0xf bound_ctrl:1
	v_fmac_f32_e32 v83, v56, v100
	v_add_f32_e32 v90, 1.0, v90
	v_rcp_f32_e32 v90, v90
	v_fmac_f32_e32 v83, v108, v98
	v_add_f32_e32 v83, v122, v83
	v_cndmask_b32_e64 v98, v57, v49, s[34:35]
	v_mul_f32_e32 v79, v79, v90
	v_mul_f32_e32 v79, v83, v79
	v_cndmask_b32_e64 v83, v61, 0, vcc
	v_cndmask_b32_e64 v90, v61, v53, s[34:35]
	v_mov_b32_dpp v99, v98 row_ror:15 row_mask:0xf bank_mask:0xf
	v_mul_f32_dpp v83, v83, v65 row_ror:1 row_mask:0xf bank_mask:0xf bound_ctrl:1
	v_fmac_f32_e32 v83, v61, v69
	v_fmac_f32_dpp v83, v90, v75 row_ror:15 row_mask:0xf bank_mask:0xf
	v_add_f32_e32 v83, v85, v83
	v_mul_f32_e32 v91, 0xbfb8aa3b, v83
	v_exp_f32_e32 v91, v91
	v_cndmask_b32_e64 v90, v57, 0, vcc
	v_add_f32_e32 v91, 1.0, v91
	v_rcp_f32_e32 v91, v91
	v_mul_f32_dpp v90, v90, v93 row_ror:1 row_mask:0xf bank_mask:0xf bound_ctrl:1
	v_fmac_f32_e32 v90, v57, v101
	v_fmac_f32_e32 v90, v109, v99
	v_add_f32_e32 v90, v123, v90
	v_mul_f32_e32 v83, v83, v91
	v_mul_f32_e32 v83, v90, v83
	v_cndmask_b32_e64 v90, v62, 0, vcc
	v_cndmask_b32_e64 v91, v62, v54, s[34:35]
	v_cndmask_b32_e64 v99, v58, v50, s[34:35]
	v_mul_f32_dpp v90, v90, v66 row_ror:1 row_mask:0xf bank_mask:0xf bound_ctrl:1
	v_fmac_f32_e32 v90, v62, v70
	v_fmac_f32_dpp v90, v91, v76 row_ror:15 row_mask:0xf bank_mask:0xf
	v_add_f32_e32 v90, v86, v90
	v_mul_f32_e32 v98, 0xbfb8aa3b, v90
	v_exp_f32_e32 v98, v98
	v_cndmask_b32_e64 v91, v58, 0, vcc
	v_mov_b32_dpp v106, v99 row_ror:15 row_mask:0xf bank_mask:0xf
	v_add_f32_e32 v98, 1.0, v98
	v_rcp_f32_e32 v98, v98
	v_mul_f32_dpp v91, v91, v94 row_ror:1 row_mask:0xf bank_mask:0xf bound_ctrl:1
	v_fmac_f32_e32 v91, v58, v102
	v_fmac_f32_e32 v91, v110, v106
	v_add_f32_e32 v91, v124, v91
	v_mul_f32_e32 v90, v90, v98
	v_mul_f32_e32 v90, v91, v90
	v_cndmask_b32_e64 v91, v63, 0, vcc
	v_cndmask_b32_e64 v98, v63, v55, s[34:35]
	v_cndmask_b32_e64 v106, v59, v51, s[34:35]
	v_mul_f32_dpp v91, v91, v67 row_ror:1 row_mask:0xf bank_mask:0xf bound_ctrl:1
	v_fmac_f32_e32 v91, v63, v71
	v_fmac_f32_dpp v91, v98, v77 row_ror:15 row_mask:0xf bank_mask:0xf
	v_add_f32_e32 v91, v87, v91
	v_mul_f32_e32 v99, 0xbfb8aa3b, v91
	v_exp_f32_e32 v99, v99
	v_cndmask_b32_e64 v98, v59, 0, vcc
	v_cvt_pk_bf16_f32 v120, v79, v83
	v_add_f32_e32 v99, 1.0, v99
	v_rcp_f32_e32 v99, v99
	v_mul_f32_dpp v98, v98, v95 row_ror:1 row_mask:0xf bank_mask:0xf bound_ctrl:1
	v_fmac_f32_e32 v98, v59, v103
	v_fmac_f32_dpp v98, v106, v111 row_ror:15 row_mask:0xf bank_mask:0xf
	v_add_f32_e32 v98, v125, v98
	v_mul_f32_e32 v91, v91, v99
	v_mul_f32_e32 v91, v98, v91
	v_cvt_pk_bf16_f32 v121, v90, v91
	global_store_dwordx4 v164, v[118:121], s[40:41]
	s_and_saveexec_b64 s[6:7], s[36:37]
	s_cbranch_execz .LBB0_1415
	v_mov_b64_e32 v[78:79], s[0:1]
	v_mad_i64_i32 v[78:79], s[88:89], v183, s66, v[78:79]
	v_lshl_add_u64 v[78:79], s[16:17], 1, v[78:79]
	s_lshl_b32 s48, s5, 1
	v_lshl_add_u64 v[78:79], v[78:79], 0, s[48:49]
	v_mov_b32_e32 v179, v165
	v_lshl_add_u64 v[78:79], v[78:79], 0, v[178:179]
	v_cvt_pk_bf16_f32 v90, v60, v61
	v_cvt_pk_bf16_f32 v91, v62, v63
	global_store_dwordx2 v[78:79], v[90:91], off offset:8
	v_cvt_pk_bf16_f32 v90, v56, v57
	v_cvt_pk_bf16_f32 v91, v58, v59
	global_store_dwordx2 v[78:79], v[90:91], off offset:264
.LBB0_1415:
	s_or_b64 exec, exec, s[6:7]
	v_cndmask_b32_e32 v60, v52, v60, vcc
	v_cndmask_b32_e64 v83, v52, v44, s[34:35]
	s_nop 0
	v_mul_f32_dpp v60, v60, v64 row_ror:1 row_mask:0xf bank_mask:0xf bound_ctrl:1
	v_fmac_f32_e32 v60, v52, v68
	v_fmac_f32_dpp v60, v83, v74 row_ror:15 row_mask:0xf bank_mask:0xf
	v_add_f32_e32 v60, v84, v60
	v_mul_f32_e32 v90, 0xbfb8aa3b, v60
	v_exp_f32_e32 v90, v90
	v_cndmask_b32_e64 v83, v48, v40, s[34:35]
	v_cndmask_b32_e32 v56, v48, v56, vcc
	v_cndmask_b32_e32 v57, v49, v57, vcc
	v_mov_b32_dpp v91, v83 row_ror:15 row_mask:0xf bank_mask:0xf
	v_add_f32_e32 v83, 1.0, v90
	v_rcp_f32_e32 v83, v83
	v_mul_f32_dpp v56, v56, v92 row_ror:1 row_mask:0xf bank_mask:0xf bound_ctrl:1
	v_fmac_f32_e32 v56, v48, v100
	v_fmac_f32_e32 v56, v108, v91
	v_add_f32_e32 v56, v122, v56
	v_mul_f32_e32 v60, v60, v83
	v_mul_f32_e32 v56, v56, v60
	v_cndmask_b32_e32 v60, v53, v61, vcc
	v_cndmask_b32_e64 v61, v53, v45, s[34:35]
	s_nop 0
	v_mul_f32_dpp v60, v60, v65 row_ror:1 row_mask:0xf bank_mask:0xf bound_ctrl:1
	v_fmac_f32_e32 v60, v53, v69
	v_fmac_f32_dpp v60, v61, v75 row_ror:15 row_mask:0xf bank_mask:0xf
	v_add_f32_e32 v60, v85, v60
	v_mul_f32_e32 v83, 0xbfb8aa3b, v60
	v_exp_f32_e32 v83, v83
	v_cndmask_b32_e64 v61, v49, v41, s[34:35]
	v_mul_f32_dpp v57, v57, v93 row_ror:1 row_mask:0xf bank_mask:0xf bound_ctrl:1
	v_fmac_f32_e32 v57, v49, v101
	v_mov_b32_dpp v90, v61 row_ror:15 row_mask:0xf bank_mask:0xf
	v_add_f32_e32 v61, 1.0, v83
	v_rcp_f32_e32 v61, v61
	v_fmac_f32_e32 v57, v109, v90
	v_add_f32_e32 v57, v123, v57
	v_mul_f32_e32 v60, v60, v61
	v_mul_f32_e32 v57, v57, v60
	v_cndmask_b32_e32 v60, v54, v62, vcc
	v_cndmask_b32_e64 v61, v54, v46, s[34:35]
	s_nop 0
	v_mul_f32_dpp v60, v60, v66 row_ror:1 row_mask:0xf bank_mask:0xf bound_ctrl:1
	v_fmac_f32_e32 v60, v54, v70
	v_fmac_f32_dpp v60, v61, v76 row_ror:15 row_mask:0xf bank_mask:0xf
	v_add_f32_e32 v60, v86, v60
	v_mul_f32_e32 v62, 0xbfb8aa3b, v60
	v_exp_f32_e32 v62, v62
	v_cndmask_b32_e64 v61, v50, v42, s[34:35]
	v_cndmask_b32_e32 v58, v50, v58, vcc
	v_cndmask_b32_e32 v52, v44, v52, vcc
	v_mov_b32_dpp v83, v61 row_ror:15 row_mask:0xf bank_mask:0xf
	v_add_f32_e32 v61, 1.0, v62
	v_rcp_f32_e32 v61, v61
	v_mul_f32_dpp v58, v58, v94 row_ror:1 row_mask:0xf bank_mask:0xf bound_ctrl:1
	v_fmac_f32_e32 v58, v50, v102
	v_fmac_f32_e32 v58, v110, v83
	v_add_f32_e32 v58, v124, v58
	v_mul_f32_e32 v60, v60, v61
	v_mul_f32_e32 v58, v58, v60
	v_cndmask_b32_e32 v60, v55, v63, vcc
	v_cndmask_b32_e64 v61, v55, v47, s[34:35]
	s_nop 0
	v_mul_f32_dpp v60, v60, v67 row_ror:1 row_mask:0xf bank_mask:0xf bound_ctrl:1
	v_fmac_f32_e32 v60, v55, v71
	v_fmac_f32_dpp v60, v61, v77 row_ror:15 row_mask:0xf bank_mask:0xf
	v_add_f32_e32 v60, v87, v60
	v_mul_f32_e32 v62, 0xbfb8aa3b, v60
	v_exp_f32_e32 v62, v62
	v_cvt_pk_bf16_f32 v118, v56, v57
	v_cndmask_b32_e64 v56, v44, v36, s[34:35]
	v_mul_f32_dpp v52, v52, v64 row_ror:1 row_mask:0xf bank_mask:0xf bound_ctrl:1
	v_cndmask_b32_e64 v61, v51, v43, s[34:35]
	v_fmac_f32_e32 v52, v44, v68
	s_nop 0
	v_mov_b32_dpp v63, v61 row_ror:15 row_mask:0xf bank_mask:0xf
	v_add_f32_e32 v61, 1.0, v62
	v_fmac_f32_dpp v52, v56, v74 row_ror:15 row_mask:0xf bank_mask:0xf
	v_cndmask_b32_e32 v59, v51, v59, vcc
	v_rcp_f32_e32 v61, v61
	v_add_f32_e32 v52, v84, v52
	v_mul_f32_dpp v59, v59, v95 row_ror:1 row_mask:0xf bank_mask:0xf bound_ctrl:1
	v_mul_f32_e32 v57, 0xbfb8aa3b, v52
	v_fmac_f32_e32 v59, v51, v103
	v_exp_f32_e32 v57, v57
	v_fmac_f32_e32 v59, v111, v63
	v_add_f32_e32 v59, v125, v59
	v_mul_f32_e32 v60, v60, v61
	v_mul_f32_e32 v59, v59, v60
	v_cvt_pk_bf16_f32 v119, v58, v59
	v_cndmask_b32_e64 v56, v40, v32, s[34:35]
	v_cndmask_b32_e32 v48, v40, v48, vcc
	v_cndmask_b32_e32 v49, v41, v49, vcc
	v_mov_b32_dpp v58, v56 row_ror:15 row_mask:0xf bank_mask:0xf
	v_add_f32_e32 v56, 1.0, v57
	v_rcp_f32_e32 v56, v56
	v_mul_f32_dpp v48, v48, v92 row_ror:1 row_mask:0xf bank_mask:0xf bound_ctrl:1
	v_fmac_f32_e32 v48, v40, v100
	v_fmac_f32_e32 v48, v108, v58
	v_add_f32_e32 v48, v122, v48
	v_mul_f32_e32 v52, v52, v56
	v_mul_f32_e32 v48, v48, v52
	v_cndmask_b32_e32 v52, v45, v53, vcc
	v_cndmask_b32_e64 v53, v45, v37, s[34:35]
	s_nop 0
	v_mul_f32_dpp v52, v52, v65 row_ror:1 row_mask:0xf bank_mask:0xf bound_ctrl:1
	v_fmac_f32_e32 v52, v45, v69
	v_fmac_f32_dpp v52, v53, v75 row_ror:15 row_mask:0xf bank_mask:0xf
	v_add_f32_e32 v52, v85, v52
	v_mul_f32_e32 v56, 0xbfb8aa3b, v52
	v_exp_f32_e32 v56, v56
	v_cndmask_b32_e64 v53, v41, v33, s[34:35]
	v_mul_f32_dpp v49, v49, v93 row_ror:1 row_mask:0xf bank_mask:0xf bound_ctrl:1
	v_fmac_f32_e32 v49, v41, v101
	v_mov_b32_dpp v57, v53 row_ror:15 row_mask:0xf bank_mask:0xf
	v_add_f32_e32 v53, 1.0, v56
	v_rcp_f32_e32 v53, v53
	v_fmac_f32_e32 v49, v109, v57
	v_add_f32_e32 v49, v123, v49
	v_mul_f32_e32 v52, v52, v53
	v_mul_f32_e32 v49, v49, v52
	v_cndmask_b32_e32 v52, v46, v54, vcc
	v_cndmask_b32_e64 v53, v46, v38, s[34:35]
	s_nop 0
	v_mul_f32_dpp v52, v52, v66 row_ror:1 row_mask:0xf bank_mask:0xf bound_ctrl:1
	v_fmac_f32_e32 v52, v46, v70
	v_fmac_f32_dpp v52, v53, v76 row_ror:15 row_mask:0xf bank_mask:0xf
	v_add_f32_e32 v52, v86, v52
	v_mul_f32_e32 v54, 0xbfb8aa3b, v52
	v_exp_f32_e32 v54, v54
	v_cndmask_b32_e64 v53, v42, v34, s[34:35]
	v_cndmask_b32_e32 v50, v42, v50, vcc
	v_cndmask_b32_e32 v51, v43, v51, vcc
	v_mov_b32_dpp v56, v53 row_ror:15 row_mask:0xf bank_mask:0xf
	v_add_f32_e32 v53, 1.0, v54
	v_rcp_f32_e32 v53, v53
	v_mul_f32_dpp v50, v50, v94 row_ror:1 row_mask:0xf bank_mask:0xf bound_ctrl:1
	v_fmac_f32_e32 v50, v42, v102
	v_fmac_f32_e32 v50, v110, v56
	v_add_f32_e32 v50, v124, v50
	v_mul_f32_e32 v52, v52, v53
	v_mul_f32_e32 v50, v50, v52
	v_cndmask_b32_e32 v52, v47, v55, vcc
	v_cndmask_b32_e64 v53, v47, v39, s[34:35]
	s_nop 0
	v_mul_f32_dpp v52, v52, v67 row_ror:1 row_mask:0xf bank_mask:0xf bound_ctrl:1
	v_fmac_f32_e32 v52, v47, v71
	v_fmac_f32_dpp v52, v53, v77 row_ror:15 row_mask:0xf bank_mask:0xf
	v_add_f32_e32 v52, v87, v52
	v_mul_f32_e32 v54, 0xbfb8aa3b, v52
	v_exp_f32_e32 v54, v54
	v_cndmask_b32_e64 v53, v43, v35, s[34:35]
	v_mul_f32_dpp v51, v51, v95 row_ror:1 row_mask:0xf bank_mask:0xf bound_ctrl:1
	v_fmac_f32_e32 v51, v43, v103
	v_mov_b32_dpp v55, v53 row_ror:15 row_mask:0xf bank_mask:0xf
	v_add_f32_e32 v53, 1.0, v54
	v_rcp_f32_e32 v53, v53
	v_fmac_f32_e32 v51, v111, v55
	v_add_f32_e32 v51, v125, v51
	v_cndmask_b32_e32 v44, v36, v44, vcc
	v_mul_f32_e32 v52, v52, v53
	v_mul_f32_e32 v51, v51, v52
	v_cvt_pk_bf16_f32 v115, v50, v51
	v_cndmask_b32_e64 v50, v36, 0, s[34:35]
	v_mul_f32_dpp v44, v44, v64 row_ror:1 row_mask:0xf bank_mask:0xf bound_ctrl:1
	v_fmac_f32_e32 v44, v36, v68
	v_fmac_f32_dpp v44, v50, v74 row_ror:15 row_mask:0xf bank_mask:0xf
	v_add_f32_e32 v44, v84, v44
	v_mul_f32_e32 v51, 0xbfb8aa3b, v44
	v_exp_f32_e32 v51, v51
	v_cndmask_b32_e64 v50, v32, 0, s[34:35]
	v_cndmask_b32_e32 v40, v32, v40, vcc
	v_cndmask_b32_e32 v41, v33, v41, vcc
	v_mov_b32_dpp v52, v50 row_ror:15 row_mask:0xf bank_mask:0xf
	v_add_f32_e32 v50, 1.0, v51
	v_rcp_f32_e32 v50, v50
	v_mul_f32_dpp v40, v40, v92 row_ror:1 row_mask:0xf bank_mask:0xf bound_ctrl:1
	v_fmac_f32_e32 v40, v32, v100
	v_fmac_f32_e32 v40, v108, v52
	v_add_f32_e32 v40, v122, v40
	v_mul_f32_e32 v44, v44, v50
	v_mul_f32_e32 v40, v40, v44
	v_cndmask_b32_e32 v44, v37, v45, vcc
	v_cndmask_b32_e64 v45, v37, 0, s[34:35]
	s_nop 0
	v_mul_f32_dpp v44, v44, v65 row_ror:1 row_mask:0xf bank_mask:0xf bound_ctrl:1
	v_fmac_f32_e32 v44, v37, v69
	v_fmac_f32_dpp v44, v45, v75 row_ror:15 row_mask:0xf bank_mask:0xf
	v_add_f32_e32 v44, v85, v44
	v_mul_f32_e32 v50, 0xbfb8aa3b, v44
	v_exp_f32_e32 v50, v50
	v_cndmask_b32_e64 v45, v33, 0, s[34:35]
	v_mul_f32_dpp v41, v41, v93 row_ror:1 row_mask:0xf bank_mask:0xf bound_ctrl:1
	v_fmac_f32_e32 v41, v33, v101
	v_mov_b32_dpp v51, v45 row_ror:15 row_mask:0xf bank_mask:0xf
	v_add_f32_e32 v45, 1.0, v50
	v_rcp_f32_e32 v45, v45
	v_fmac_f32_e32 v41, v109, v51
	v_add_f32_e32 v41, v123, v41
	v_mul_f32_e32 v44, v44, v45
	v_mul_f32_e32 v41, v41, v44
	v_cndmask_b32_e32 v44, v38, v46, vcc
	v_cndmask_b32_e64 v45, v38, 0, s[34:35]
	s_nop 0
	v_mul_f32_dpp v44, v44, v66 row_ror:1 row_mask:0xf bank_mask:0xf bound_ctrl:1
	v_fmac_f32_e32 v44, v38, v70
	v_fmac_f32_dpp v44, v45, v76 row_ror:15 row_mask:0xf bank_mask:0xf
	v_add_f32_e32 v44, v86, v44
	v_mul_f32_e32 v46, 0xbfb8aa3b, v44
	v_exp_f32_e32 v46, v46
	v_cndmask_b32_e64 v45, v34, 0, s[34:35]
	v_cndmask_b32_e32 v42, v34, v42, vcc
	v_cndmask_b32_e32 v43, v35, v43, vcc
	v_mov_b32_dpp v50, v45 row_ror:15 row_mask:0xf bank_mask:0xf
	v_add_f32_e32 v45, 1.0, v46
	v_rcp_f32_e32 v45, v45
	v_mul_f32_dpp v42, v42, v94 row_ror:1 row_mask:0xf bank_mask:0xf bound_ctrl:1
	v_fmac_f32_e32 v42, v34, v102
	v_fmac_f32_e32 v42, v110, v50
	v_add_f32_e32 v42, v124, v42
	v_mul_f32_e32 v44, v44, v45
	v_mul_f32_e32 v42, v42, v44
	v_cndmask_b32_e32 v44, v39, v47, vcc
	v_cndmask_b32_e64 v45, v39, 0, s[34:35]
	s_nop 0
	v_mul_f32_dpp v44, v44, v67 row_ror:1 row_mask:0xf bank_mask:0xf bound_ctrl:1
	v_fmac_f32_e32 v44, v39, v71
	v_fmac_f32_dpp v44, v45, v77 row_ror:15 row_mask:0xf bank_mask:0xf
	v_add_f32_e32 v44, v87, v44
	v_mul_f32_e32 v46, 0xbfb8aa3b, v44
	v_exp_f32_e32 v46, v46
	v_cndmask_b32_e64 v45, v35, 0, s[34:35]
	v_mul_f32_dpp v43, v43, v95 row_ror:1 row_mask:0xf bank_mask:0xf bound_ctrl:1
	v_lshl_add_u64 v[78:79], s[40:41], 0, v[164:165]
	v_mov_b32_dpp v47, v45 row_ror:15 row_mask:0xf bank_mask:0xf
	v_add_f32_e32 v45, 1.0, v46
	v_rcp_f32_e32 v45, v45
	s_movk_i32 s6, 0x1000
	v_fmac_f32_e32 v43, v35, v103
	v_cvt_pk_bf16_f32 v114, v48, v49
	v_add_co_u32_e64 v48, s[40:41], s6, v78
	v_fmac_f32_e32 v43, v111, v47
	s_nop 0
	v_addc_co_u32_e64 v49, s[40:41], 0, v79, s[40:41]
	v_add_f32_e32 v43, v125, v43
	v_mul_f32_e32 v44, v44, v45
	global_store_dwordx4 v[78:79], v[116:119], off offset:2048
	global_store_dwordx4 v[48:49], v[112:115], off
	v_mul_f32_e32 v43, v43, v44
	v_cvt_pk_bf16_f32 v106, v40, v41
	v_cvt_pk_bf16_f32 v107, v42, v43
	global_store_dwordx4 v[48:49], v[104:107], off offset:2048
	s_and_saveexec_b64 s[40:41], s[38:39]
	s_cbranch_execz .LBB0_1417
	v_mov_b32_e32 v181, v165
	v_lshl_add_u64 v[40:41], s[52:53], 0, v[180:181]
	v_mov_b64_e32 v[42:43], s[0:1]
	s_movk_i32 s31, 0x2c00
	v_mad_u64_u32 v[42:43], s[6:7], v40, s31, v[42:43]
	v_mad_i32_i24 v43, v41, s31, v43
	v_lshl_add_u64 v[40:41], s[16:17], 1, v[42:43]
	s_lshl_b32 s48, s5, 1
	v_lshl_add_u64 v[40:41], v[40:41], 0, s[48:49]
	v_mov_b32_e32 v179, v165
	s_movk_i32 s66, 0x2c00
	v_lshl_add_u64 v[40:41], v[40:41], 0, v[178:179]
	v_cvt_pk_bf16_f32 v36, v36, v37
	v_cvt_pk_bf16_f32 v37, v38, v39
	global_store_dwordx2 v[40:41], v[36:37], off offset:8
	v_cvt_pk_bf16_f32 v32, v32, v33
	v_cvt_pk_bf16_f32 v33, v34, v35
	global_store_dwordx2 v[40:41], v[32:33], off offset:264
.LBB0_1417:
	s_or_b64 exec, exec, s[40:41]
	v_cndmask_b32_e64 v33, v28, 0, vcc
	v_cndmask_b32_e64 v34, v28, v20, s[34:35]
	s_nop 0
	v_mul_f32_dpp v33, v33, v64 row_ror:1 row_mask:0xf bank_mask:0xf bound_ctrl:1
	v_fmac_f32_e32 v33, v28, v68
	v_fmac_f32_dpp v33, v34, v74 row_ror:15 row_mask:0xf bank_mask:0xf
	v_add_f32_e32 v33, v84, v33
	v_mul_f32_e32 v35, 0xbfb8aa3b, v33
	v_exp_f32_e32 v35, v35
	v_cndmask_b32_e64 v34, v24, 0, vcc
	v_cndmask_b32_e64 v36, v24, v16, s[34:35]
	v_add_f32_e32 v35, 1.0, v35
	v_rcp_f32_e32 v35, v35
	v_mul_f32_dpp v34, v34, v92 row_ror:1 row_mask:0xf bank_mask:0xf bound_ctrl:1
	v_fmac_f32_e32 v34, v24, v100
	v_fmac_f32_dpp v34, v36, v108 row_ror:15 row_mask:0xf bank_mask:0xf
	v_add_f32_e32 v34, v122, v34
	v_mul_f32_e32 v33, v33, v35
	v_mul_f32_e32 v33, v34, v33
	v_cndmask_b32_e64 v34, v29, 0, vcc
	v_cndmask_b32_e64 v35, v29, v21, s[34:35]
	s_nop 0
	v_mul_f32_dpp v34, v34, v65 row_ror:1 row_mask:0xf bank_mask:0xf bound_ctrl:1
	v_fmac_f32_e32 v34, v29, v69
	v_fmac_f32_dpp v34, v35, v75 row_ror:15 row_mask:0xf bank_mask:0xf
	v_add_f32_e32 v34, v85, v34
	v_mul_f32_e32 v36, 0xbfb8aa3b, v34
	v_exp_f32_e32 v36, v36
	v_cndmask_b32_e64 v35, v25, 0, vcc
	v_cndmask_b32_e64 v37, v25, v17, s[34:35]
	v_add_f32_e32 v36, 1.0, v36
	v_rcp_f32_e32 v36, v36
	v_mul_f32_dpp v35, v35, v93 row_ror:1 row_mask:0xf bank_mask:0xf bound_ctrl:1
	v_fmac_f32_e32 v35, v25, v101
	v_fmac_f32_dpp v35, v37, v109 row_ror:15 row_mask:0xf bank_mask:0xf
	v_add_f32_e32 v35, v123, v35
	v_mul_f32_e32 v34, v34, v36
	v_mul_f32_e32 v34, v35, v34
	v_cndmask_b32_e64 v35, v30, 0, vcc
	v_cndmask_b32_e64 v36, v30, v22, s[34:35]
	s_nop 0
	v_mul_f32_dpp v35, v35, v66 row_ror:1 row_mask:0xf bank_mask:0xf bound_ctrl:1
	v_fmac_f32_e32 v35, v30, v70
	v_fmac_f32_dpp v35, v36, v76 row_ror:15 row_mask:0xf bank_mask:0xf
	v_add_f32_e32 v35, v86, v35
	v_mul_f32_e32 v37, 0xbfb8aa3b, v35
	v_exp_f32_e32 v37, v37
	v_cndmask_b32_e64 v36, v26, 0, vcc
	v_cndmask_b32_e64 v38, v26, v18, s[34:35]
	v_add_f32_e32 v37, 1.0, v37
	v_rcp_f32_e32 v37, v37
	v_mul_f32_dpp v36, v36, v94 row_ror:1 row_mask:0xf bank_mask:0xf bound_ctrl:1
	v_fmac_f32_e32 v36, v26, v102
	v_fmac_f32_dpp v36, v38, v110 row_ror:15 row_mask:0xf bank_mask:0xf
	v_add_f32_e32 v36, v124, v36
	v_mul_f32_e32 v35, v35, v37
	v_mul_f32_e32 v35, v36, v35
	v_cndmask_b32_e64 v36, v31, 0, vcc
	v_cndmask_b32_e64 v37, v31, v23, s[34:35]
	s_nop 0
	v_mul_f32_dpp v36, v36, v67 row_ror:1 row_mask:0xf bank_mask:0xf bound_ctrl:1
	v_fmac_f32_e32 v36, v31, v71
	v_fmac_f32_dpp v36, v37, v77 row_ror:15 row_mask:0xf bank_mask:0xf
	v_add_f32_e32 v36, v87, v36
	v_mul_f32_e32 v38, 0xbfb8aa3b, v36
	v_exp_f32_e32 v38, v38
	v_cndmask_b32_e64 v37, v27, 0, vcc
	v_or_b32_e32 v32, s85, v200
	s_ashr_i32 s6, s85, 8
	v_add_f32_e32 v38, 1.0, v38
	v_rcp_f32_e32 v38, v38
	v_cndmask_b32_e64 v39, v27, v19, s[34:35]
	v_mul_f32_dpp v37, v37, v95 row_ror:1 row_mask:0xf bank_mask:0xf bound_ctrl:1
	s_mul_hi_i32 s7, s6, 0x160000
	s_mul_i32 s6, s6, 0x160000
	v_mov_b32_dpp v40, v39 row_ror:15 row_mask:0xf bank_mask:0xf
	v_fmac_f32_e32 v37, v27, v103
	v_lshlrev_b32_e32 v32, 6, v32
	s_movk_i32 s31, 0x33c0
	v_fmac_f32_e32 v37, v111, v40
	v_and_or_b32 v32, v32, s31, v82
	s_add_u32 s40, s86, s6
	v_add_f32_e32 v37, v125, v37
	v_mul_f32_e32 v36, v36, v38
	s_addc_u32 s41, s87, s7
	v_lshlrev_b32_e32 v164, 1, v32
	v_mul_f32_e32 v36, v37, v36
	v_cvt_pk_bf16_f32 v98, v33, v34
	v_cvt_pk_bf16_f32 v99, v35, v36
	global_store_dwordx4 v164, v[96:99], s[40:41]
	s_and_saveexec_b64 s[6:7], s[36:37]
	s_cbranch_execz .LBB0_1419
	v_mov_b64_e32 v[32:33], s[0:1]
	v_mad_i64_i32 v[32:33], s[36:37], v156, s66, v[32:33]
	v_lshl_add_u64 v[32:33], s[16:17], 1, v[32:33]
	s_lshl_b32 s48, s5, 1
	v_lshl_add_u64 v[32:33], v[32:33], 0, s[48:49]
	v_mov_b32_e32 v179, v165
	v_lshl_add_u64 v[32:33], v[32:33], 0, v[178:179]
	v_cvt_pk_bf16_f32 v34, v28, v29
	v_cvt_pk_bf16_f32 v35, v30, v31
	global_store_dwordx2 v[32:33], v[34:35], off offset:8
	v_cvt_pk_bf16_f32 v34, v24, v25
	v_cvt_pk_bf16_f32 v35, v26, v27
	global_store_dwordx2 v[32:33], v[34:35], off offset:264
.LBB0_1419:
	s_or_b64 exec, exec, s[6:7]
	v_cndmask_b32_e32 v28, v20, v28, vcc
	v_cndmask_b32_e64 v34, v20, v12, s[34:35]
	s_nop 0
	v_mul_f32_dpp v28, v28, v64 row_ror:1 row_mask:0xf bank_mask:0xf bound_ctrl:1
	v_fmac_f32_e32 v28, v20, v68
	v_fmac_f32_dpp v28, v34, v74 row_ror:15 row_mask:0xf bank_mask:0xf
	v_add_f32_e32 v28, v84, v28
	v_mul_f32_e32 v35, 0xbfb8aa3b, v28
	v_exp_f32_e32 v35, v35
	v_cndmask_b32_e64 v34, v16, v8, s[34:35]
	v_cndmask_b32_e32 v24, v16, v24, vcc
	v_cndmask_b32_e32 v25, v17, v25, vcc
	v_mov_b32_dpp v36, v34 row_ror:15 row_mask:0xf bank_mask:0xf
	v_add_f32_e32 v34, 1.0, v35
	v_rcp_f32_e32 v34, v34
	v_mul_f32_dpp v24, v24, v92 row_ror:1 row_mask:0xf bank_mask:0xf bound_ctrl:1
	v_fmac_f32_e32 v24, v16, v100
	v_fmac_f32_e32 v24, v108, v36
	v_add_f32_e32 v24, v122, v24
	v_mul_f32_e32 v28, v28, v34
	v_mul_f32_e32 v24, v24, v28
	v_cndmask_b32_e32 v28, v21, v29, vcc
	v_cndmask_b32_e64 v29, v21, v13, s[34:35]
	s_nop 0
	v_mul_f32_dpp v28, v28, v65 row_ror:1 row_mask:0xf bank_mask:0xf bound_ctrl:1
	v_fmac_f32_e32 v28, v21, v69
	v_fmac_f32_dpp v28, v29, v75 row_ror:15 row_mask:0xf bank_mask:0xf
	v_add_f32_e32 v28, v85, v28
	v_mul_f32_e32 v34, 0xbfb8aa3b, v28
	v_exp_f32_e32 v34, v34
	v_cndmask_b32_e64 v29, v17, v9, s[34:35]
	v_mul_f32_dpp v25, v25, v93 row_ror:1 row_mask:0xf bank_mask:0xf bound_ctrl:1
	v_fmac_f32_e32 v25, v17, v101
	v_mov_b32_dpp v35, v29 row_ror:15 row_mask:0xf bank_mask:0xf
	v_add_f32_e32 v29, 1.0, v34
	v_rcp_f32_e32 v29, v29
	v_fmac_f32_e32 v25, v109, v35
	v_add_f32_e32 v25, v123, v25
	v_mul_f32_e32 v28, v28, v29
	v_mul_f32_e32 v25, v25, v28
	v_cndmask_b32_e32 v28, v22, v30, vcc
	v_cndmask_b32_e64 v29, v22, v14, s[34:35]
	s_nop 0
	v_mul_f32_dpp v28, v28, v66 row_ror:1 row_mask:0xf bank_mask:0xf bound_ctrl:1
	v_fmac_f32_e32 v28, v22, v70
	v_fmac_f32_dpp v28, v29, v76 row_ror:15 row_mask:0xf bank_mask:0xf
	v_add_f32_e32 v28, v86, v28
	v_mul_f32_e32 v30, 0xbfb8aa3b, v28
	v_exp_f32_e32 v30, v30
	v_cndmask_b32_e64 v29, v18, v10, s[34:35]
	v_cndmask_b32_e32 v26, v18, v26, vcc
	v_cndmask_b32_e32 v20, v12, v20, vcc
	v_mov_b32_dpp v34, v29 row_ror:15 row_mask:0xf bank_mask:0xf
	v_add_f32_e32 v29, 1.0, v30
	v_rcp_f32_e32 v29, v29
	v_mul_f32_dpp v26, v26, v94 row_ror:1 row_mask:0xf bank_mask:0xf bound_ctrl:1
	v_fmac_f32_e32 v26, v18, v102
	v_fmac_f32_e32 v26, v110, v34
	v_add_f32_e32 v26, v124, v26
	v_mul_f32_e32 v28, v28, v29
	v_mul_f32_e32 v26, v26, v28
	v_cndmask_b32_e32 v28, v23, v31, vcc
	v_cndmask_b32_e64 v29, v23, v15, s[34:35]
	s_nop 0
	v_mul_f32_dpp v28, v28, v67 row_ror:1 row_mask:0xf bank_mask:0xf bound_ctrl:1
	v_fmac_f32_e32 v28, v23, v71
	v_fmac_f32_dpp v28, v29, v77 row_ror:15 row_mask:0xf bank_mask:0xf
	v_add_f32_e32 v28, v87, v28
	v_mul_f32_e32 v30, 0xbfb8aa3b, v28
	v_exp_f32_e32 v30, v30
	v_cvt_pk_bf16_f32 v90, v24, v25
	v_cndmask_b32_e64 v24, v12, v4, s[34:35]
	v_mul_f32_dpp v20, v20, v64 row_ror:1 row_mask:0xf bank_mask:0xf bound_ctrl:1
	v_cndmask_b32_e64 v29, v19, v11, s[34:35]
	v_fmac_f32_e32 v20, v12, v68
	s_nop 0
	v_mov_b32_dpp v31, v29 row_ror:15 row_mask:0xf bank_mask:0xf
	v_add_f32_e32 v29, 1.0, v30
	v_fmac_f32_dpp v20, v24, v74 row_ror:15 row_mask:0xf bank_mask:0xf
	v_cndmask_b32_e32 v27, v19, v27, vcc
	v_rcp_f32_e32 v29, v29
	v_add_f32_e32 v20, v84, v20
	v_mul_f32_dpp v27, v27, v95 row_ror:1 row_mask:0xf bank_mask:0xf bound_ctrl:1
	v_mul_f32_e32 v25, 0xbfb8aa3b, v20
	v_fmac_f32_e32 v27, v19, v103
	v_exp_f32_e32 v25, v25
	v_fmac_f32_e32 v27, v111, v31
	v_add_f32_e32 v27, v125, v27
	v_mul_f32_e32 v28, v28, v29
	v_mul_f32_e32 v27, v27, v28
	v_cvt_pk_bf16_f32 v91, v26, v27
	v_cndmask_b32_e64 v24, v8, v0, s[34:35]
	v_cndmask_b32_e32 v16, v8, v16, vcc
	v_cndmask_b32_e32 v17, v9, v17, vcc
	v_mov_b32_dpp v26, v24 row_ror:15 row_mask:0xf bank_mask:0xf
	v_add_f32_e32 v24, 1.0, v25
	v_rcp_f32_e32 v24, v24
	v_mul_f32_dpp v16, v16, v92 row_ror:1 row_mask:0xf bank_mask:0xf bound_ctrl:1
	v_fmac_f32_e32 v16, v8, v100
	v_fmac_f32_e32 v16, v108, v26
	v_add_f32_e32 v16, v122, v16
	v_mul_f32_e32 v20, v20, v24
	v_mul_f32_e32 v16, v16, v20
	v_cndmask_b32_e32 v20, v13, v21, vcc
	v_cndmask_b32_e64 v21, v13, v5, s[34:35]
	s_nop 0
	v_mul_f32_dpp v20, v20, v65 row_ror:1 row_mask:0xf bank_mask:0xf bound_ctrl:1
	v_fmac_f32_e32 v20, v13, v69
	v_fmac_f32_dpp v20, v21, v75 row_ror:15 row_mask:0xf bank_mask:0xf
	v_add_f32_e32 v20, v85, v20
	v_mul_f32_e32 v24, 0xbfb8aa3b, v20
	v_exp_f32_e32 v24, v24
	v_cndmask_b32_e64 v21, v9, v1, s[34:35]
	v_mul_f32_dpp v17, v17, v93 row_ror:1 row_mask:0xf bank_mask:0xf bound_ctrl:1
	v_fmac_f32_e32 v17, v9, v101
	v_mov_b32_dpp v25, v21 row_ror:15 row_mask:0xf bank_mask:0xf
	v_add_f32_e32 v21, 1.0, v24
	v_rcp_f32_e32 v21, v21
	v_fmac_f32_e32 v17, v109, v25
	v_add_f32_e32 v17, v123, v17
	v_mul_f32_e32 v20, v20, v21
	v_mul_f32_e32 v17, v17, v20
	v_cndmask_b32_e32 v20, v14, v22, vcc
	v_cndmask_b32_e64 v21, v14, v6, s[34:35]
	s_nop 0
	v_mul_f32_dpp v20, v20, v66 row_ror:1 row_mask:0xf bank_mask:0xf bound_ctrl:1
	v_fmac_f32_e32 v20, v14, v70
	v_fmac_f32_dpp v20, v21, v76 row_ror:15 row_mask:0xf bank_mask:0xf
	v_add_f32_e32 v20, v86, v20
	v_mul_f32_e32 v22, 0xbfb8aa3b, v20
	v_exp_f32_e32 v22, v22
	v_cndmask_b32_e64 v21, v10, v2, s[34:35]
	v_cndmask_b32_e32 v18, v10, v18, vcc
	v_cndmask_b32_e32 v19, v11, v19, vcc
	v_mov_b32_dpp v24, v21 row_ror:15 row_mask:0xf bank_mask:0xf
	v_add_f32_e32 v21, 1.0, v22
	v_rcp_f32_e32 v21, v21
	v_mul_f32_dpp v18, v18, v94 row_ror:1 row_mask:0xf bank_mask:0xf bound_ctrl:1
	v_fmac_f32_e32 v18, v10, v102
	v_fmac_f32_e32 v18, v110, v24
	v_add_f32_e32 v18, v124, v18
	v_mul_f32_e32 v20, v20, v21
	v_mul_f32_e32 v18, v18, v20
	v_cndmask_b32_e32 v20, v15, v23, vcc
	v_cndmask_b32_e64 v21, v15, v7, s[34:35]
	s_nop 0
	v_mul_f32_dpp v20, v20, v67 row_ror:1 row_mask:0xf bank_mask:0xf bound_ctrl:1
	v_fmac_f32_e32 v20, v15, v71
	v_fmac_f32_dpp v20, v21, v77 row_ror:15 row_mask:0xf bank_mask:0xf
	v_add_f32_e32 v20, v87, v20
	v_mul_f32_e32 v22, 0xbfb8aa3b, v20
	v_exp_f32_e32 v22, v22
	v_cndmask_b32_e64 v21, v11, v3, s[34:35]
	v_mul_f32_dpp v19, v19, v95 row_ror:1 row_mask:0xf bank_mask:0xf bound_ctrl:1
	v_fmac_f32_e32 v19, v11, v103
	v_mov_b32_dpp v23, v21 row_ror:15 row_mask:0xf bank_mask:0xf
	v_add_f32_e32 v21, 1.0, v22
	v_rcp_f32_e32 v21, v21
	v_fmac_f32_e32 v19, v111, v23
	v_add_f32_e32 v19, v125, v19
	v_cndmask_b32_e32 v12, v4, v12, vcc
	v_mul_f32_e32 v20, v20, v21
	v_mul_f32_e32 v19, v19, v20
	v_cvt_pk_bf16_f32 v83, v18, v19
	v_cndmask_b32_e64 v18, v4, 0, s[34:35]
	v_mul_f32_dpp v12, v12, v64 row_ror:1 row_mask:0xf bank_mask:0xf bound_ctrl:1
	v_fmac_f32_e32 v12, v4, v68
	v_fmac_f32_dpp v12, v18, v74 row_ror:15 row_mask:0xf bank_mask:0xf
	v_add_f32_e32 v12, v84, v12
	v_mul_f32_e32 v19, 0xbfb8aa3b, v12
	v_exp_f32_e32 v19, v19
	v_cndmask_b32_e64 v18, v0, 0, s[34:35]
	v_cndmask_b32_e32 v8, v0, v8, vcc
	v_cndmask_b32_e32 v9, v1, v9, vcc
	v_mov_b32_dpp v20, v18 row_ror:15 row_mask:0xf bank_mask:0xf
	v_add_f32_e32 v18, 1.0, v19
	v_rcp_f32_e32 v18, v18
	v_mul_f32_dpp v8, v8, v92 row_ror:1 row_mask:0xf bank_mask:0xf bound_ctrl:1
	v_fmac_f32_e32 v8, v0, v100
	v_fmac_f32_e32 v8, v108, v20
	v_add_f32_e32 v8, v122, v8
	v_mul_f32_e32 v12, v12, v18
	v_mul_f32_e32 v8, v8, v12
	v_cndmask_b32_e32 v12, v5, v13, vcc
	v_cndmask_b32_e64 v13, v5, 0, s[34:35]
	s_nop 0
	v_mul_f32_dpp v12, v12, v65 row_ror:1 row_mask:0xf bank_mask:0xf bound_ctrl:1
	v_fmac_f32_e32 v12, v5, v69
	v_fmac_f32_dpp v12, v13, v75 row_ror:15 row_mask:0xf bank_mask:0xf
	v_add_f32_e32 v12, v85, v12
	v_mul_f32_e32 v18, 0xbfb8aa3b, v12
	v_exp_f32_e32 v18, v18
	v_cndmask_b32_e64 v13, v1, 0, s[34:35]
	v_mul_f32_dpp v9, v9, v93 row_ror:1 row_mask:0xf bank_mask:0xf bound_ctrl:1
	v_fmac_f32_e32 v9, v1, v101
	v_mov_b32_dpp v19, v13 row_ror:15 row_mask:0xf bank_mask:0xf
	v_add_f32_e32 v13, 1.0, v18
	v_rcp_f32_e32 v13, v13
	v_fmac_f32_e32 v9, v109, v19
	v_add_f32_e32 v9, v123, v9
	v_mul_f32_e32 v12, v12, v13
	v_mul_f32_e32 v9, v9, v12
	v_cndmask_b32_e32 v12, v6, v14, vcc
	v_cndmask_b32_e64 v13, v6, 0, s[34:35]
	s_nop 0
	v_mul_f32_dpp v12, v12, v66 row_ror:1 row_mask:0xf bank_mask:0xf bound_ctrl:1
	v_fmac_f32_e32 v12, v6, v70
	v_fmac_f32_dpp v12, v13, v76 row_ror:15 row_mask:0xf bank_mask:0xf
	v_add_f32_e32 v12, v86, v12
	v_mul_f32_e32 v14, 0xbfb8aa3b, v12
	v_exp_f32_e32 v14, v14
	v_cndmask_b32_e64 v13, v2, 0, s[34:35]
	v_cndmask_b32_e32 v10, v2, v10, vcc
	v_cndmask_b32_e32 v11, v3, v11, vcc
	v_mov_b32_dpp v18, v13 row_ror:15 row_mask:0xf bank_mask:0xf
	v_add_f32_e32 v13, 1.0, v14
	v_rcp_f32_e32 v13, v13
	v_mul_f32_dpp v10, v10, v94 row_ror:1 row_mask:0xf bank_mask:0xf bound_ctrl:1
	v_fmac_f32_e32 v10, v2, v102
	v_fmac_f32_e32 v10, v110, v18
	v_add_f32_e32 v10, v124, v10
	v_mul_f32_e32 v12, v12, v13
	v_mul_f32_e32 v10, v10, v12
	v_cndmask_b32_e32 v12, v7, v15, vcc
	v_cndmask_b32_e64 v13, v7, 0, s[34:35]
	s_nop 0
	v_mul_f32_dpp v12, v12, v67 row_ror:1 row_mask:0xf bank_mask:0xf bound_ctrl:1
	v_fmac_f32_e32 v12, v7, v71
	v_fmac_f32_dpp v12, v13, v77 row_ror:15 row_mask:0xf bank_mask:0xf
	v_add_f32_e32 v12, v87, v12
	v_mul_f32_e32 v14, 0xbfb8aa3b, v12
	v_exp_f32_e32 v14, v14
	v_cndmask_b32_e64 v13, v3, 0, s[34:35]
	v_mul_f32_dpp v11, v11, v95 row_ror:1 row_mask:0xf bank_mask:0xf bound_ctrl:1
	v_lshl_add_u64 v[32:33], s[40:41], 0, v[164:165]
	v_mov_b32_dpp v15, v13 row_ror:15 row_mask:0xf bank_mask:0xf
	v_add_f32_e32 v13, 1.0, v14
	v_rcp_f32_e32 v13, v13
	s_movk_i32 s6, 0x1000
	v_fmac_f32_e32 v11, v3, v103
	v_cvt_pk_bf16_f32 v82, v16, v17
	v_add_co_u32_e64 v16, s[36:37], s6, v32
	v_fmac_f32_e32 v11, v111, v15
	s_nop 0
	v_addc_co_u32_e64 v17, s[36:37], 0, v33, s[36:37]
	v_add_f32_e32 v11, v125, v11
	v_mul_f32_e32 v12, v12, v13
	global_store_dwordx4 v[32:33], v[88:91], off offset:2048
	global_store_dwordx4 v[16:17], v[80:83], off
	v_mul_f32_e32 v11, v11, v12
	v_cvt_pk_bf16_f32 v74, v8, v9
	v_cvt_pk_bf16_f32 v75, v10, v11
	global_store_dwordx4 v[16:17], v[72:75], off offset:2048
	s_and_saveexec_b64 s[34:35], s[38:39]
	s_cbranch_execz .LBB0_1392
	v_mov_b32_e32 v181, v165
	v_lshl_add_u64 v[8:9], s[10:11], 0, v[180:181]
	v_mov_b64_e32 v[10:11], s[0:1]
	s_movk_i32 s10, 0x2c00
	v_mad_u64_u32 v[10:11], s[6:7], v8, s10, v[10:11]
	v_mad_i32_i24 v11, v9, s10, v11
	v_lshl_add_u64 v[8:9], s[16:17], 1, v[10:11]
	s_lshl_b32 s48, s5, 1
	v_lshl_add_u64 v[8:9], v[8:9], 0, s[48:49]
	v_mov_b32_e32 v179, v165
	s_movk_i32 s66, 0x2c00
	v_lshl_add_u64 v[8:9], v[8:9], 0, v[178:179]
	v_cvt_pk_bf16_f32 v4, v4, v5
	v_cvt_pk_bf16_f32 v5, v6, v7
	global_store_dwordx2 v[8:9], v[4:5], off offset:8
	v_cvt_pk_bf16_f32 v0, v0, v1
	v_cvt_pk_bf16_f32 v1, v2, v3
	global_store_dwordx2 v[8:9], v[0:1], off offset:264
	s_branch .LBB0_1392
